# v16 plus: redundant post-barrier s_waitcnt lgkmcnt(0) removed from the GEMM K-loop MFMA segments
# baseline (speedup 1.0000x reference)
.LBB0_230:
	s_add_u32 s28, s0, 0xfff00080
	s_addc_u32 s29, s1, -1
	s_add_i32 s51, 0, 0x10000
	s_cmp_eq_u32 s50, 60
	s_cselect_b32 s31, s34, s29
	s_cselect_b32 s30, s35, s28
	v_add_u32_e32 v0, s51, v179
	s_cselect_b32 s29, s27, s43
	s_cselect_b32 s28, s40, s41
	s_add_i32 s77, 0, 0x14000
	ds_read_b128 v[130:133], v0
	ds_read_b128 v[134:137], v0 offset:1024
	ds_read_b128 v[138:141], v0 offset:2048
	ds_read_b128 v[142:145], v0 offset:3072
	v_add_u32_e32 v0, s77, v179
	ds_read_b128 v[146:149], v0
	ds_read_b128 v[150:153], v0 offset:1024
	ds_read_b128 v[154:157], v0 offset:2048
	ds_read_b128 v[158:161], v0 offset:3072
	v_lshl_add_u64 v[194:195], s[0:1], 0, v[170:171]
	s_add_i32 m0, s14, 0xc000
	ds_read_b128 v[174:177], v192
	ds_read_b128 v[180:183], v192 offset:1024
	ds_read_b128 v[184:187], v192 offset:2048
	ds_read_b128 v[188:191], v192 offset:3072
	ds_read_b128 v[200:203], v192 offset:4096
	ds_read_b128 v[204:207], v192 offset:5120
	ds_read_b128 v[208:211], v192 offset:6144
	ds_read_b128 v[212:215], v192 offset:7168
	global_load_lds_dwordx4 v[194:195], off
	v_lshl_add_u64 v[194:195], s[0:1], 0, v[172:173]
	s_add_i32 m0, s14, 0xe000
	s_nop 0
	global_load_lds_dwordx4 v[194:195], off
	s_waitcnt vmcnt(8)
	s_waitcnt lgkmcnt(0)
	s_barrier
	v_mfma_f32_16x16x32_bf16 v[126:129], v[130:133], v[174:177], v[126:129]
	v_mfma_f32_16x16x32_bf16 v[126:129], v[134:137], v[180:183], v[126:129]
	v_mfma_f32_16x16x32_bf16 v[122:125], v[138:141], v[174:177], v[122:125]
	v_mfma_f32_16x16x32_bf16 v[122:125], v[142:145], v[180:183], v[122:125]
	v_mfma_f32_16x16x32_bf16 v[110:113], v[130:133], v[184:187], v[110:113]
	v_mfma_f32_16x16x32_bf16 v[110:113], v[134:137], v[188:191], v[110:113]
	v_mfma_f32_16x16x32_bf16 v[106:109], v[138:141], v[184:187], v[106:109]
	v_mfma_f32_16x16x32_bf16 v[106:109], v[142:145], v[188:191], v[106:109]
	v_mfma_f32_16x16x32_bf16 v[94:97], v[130:133], v[200:203], v[94:97]
	v_mfma_f32_16x16x32_bf16 v[94:97], v[134:137], v[204:207], v[94:97]
	v_mfma_f32_16x16x32_bf16 v[90:93], v[138:141], v[200:203], v[90:93]
	v_mfma_f32_16x16x32_bf16 v[90:93], v[142:145], v[204:207], v[90:93]
	v_mfma_f32_16x16x32_bf16 v[78:81], v[130:133], v[208:211], v[78:81]
	v_mfma_f32_16x16x32_bf16 v[78:81], v[134:137], v[212:215], v[78:81]
	v_mfma_f32_16x16x32_bf16 v[74:77], v[138:141], v[208:211], v[74:77]
	v_mfma_f32_16x16x32_bf16 v[74:77], v[142:145], v[212:215], v[74:77]
	v_mfma_f32_16x16x32_bf16 v[118:121], v[146:149], v[174:177], v[118:121]
	v_mfma_f32_16x16x32_bf16 v[118:121], v[150:153], v[180:183], v[118:121]
	v_mfma_f32_16x16x32_bf16 v[114:117], v[154:157], v[174:177], v[114:117]
	v_mfma_f32_16x16x32_bf16 v[114:117], v[158:161], v[180:183], v[114:117]
	v_mfma_f32_16x16x32_bf16 v[102:105], v[146:149], v[184:187], v[102:105]
	v_mfma_f32_16x16x32_bf16 v[102:105], v[150:153], v[188:191], v[102:105]
	v_mfma_f32_16x16x32_bf16 v[98:101], v[154:157], v[184:187], v[98:101]
	v_mfma_f32_16x16x32_bf16 v[98:101], v[158:161], v[188:191], v[98:101]
	v_mfma_f32_16x16x32_bf16 v[86:89], v[146:149], v[200:203], v[86:89]
	v_mfma_f32_16x16x32_bf16 v[86:89], v[150:153], v[204:207], v[86:89]
	v_mfma_f32_16x16x32_bf16 v[82:85], v[154:157], v[200:203], v[82:85]
	v_mfma_f32_16x16x32_bf16 v[82:85], v[158:161], v[204:207], v[82:85]
	v_mfma_f32_16x16x32_bf16 v[70:73], v[146:149], v[208:211], v[70:73]
	v_mfma_f32_16x16x32_bf16 v[70:73], v[150:153], v[212:215], v[70:73]
	v_mfma_f32_16x16x32_bf16 v[66:69], v[154:157], v[208:211], v[66:69]
	v_mfma_f32_16x16x32_bf16 v[66:69], v[158:161], v[212:215], v[66:69]
	s_barrier
	s_add_i32 s51, s51, s9
	v_lshl_add_u64 v[194:195], s[28:29], 0, v[166:167]
	s_mov_b32 m0, s51
	ds_read_b128 v[174:177], v192 offset:16384
	ds_read_b128 v[180:183], v192 offset:17408
	ds_read_b128 v[184:187], v192 offset:18432
	ds_read_b128 v[188:191], v192 offset:19456
	ds_read_b128 v[200:203], v192 offset:20480
	ds_read_b128 v[204:207], v192 offset:21504
	ds_read_b128 v[208:211], v192 offset:22528
	ds_read_b128 v[212:215], v192 offset:23552
	global_load_lds_dwordx4 v[194:195], off
	s_add_i32 m0, s51, 0x2000
	s_add_u32 s80, s28, 0x100000
	v_lshl_add_u64 v[216:217], s[28:29], 0, v[162:163]
	s_addc_u32 s81, s29, 0
	s_add_i32 s51, s77, s9
	global_load_lds_dwordx4 v[216:217], off
	v_lshl_add_u64 v[218:219], s[80:81], 0, v[166:167]
	s_mov_b32 m0, s51
	v_lshl_add_u64 v[220:221], s[30:31], 0, v[164:165]
	global_load_lds_dwordx4 v[218:219], off
	v_lshl_add_u64 v[218:219], s[80:81], 0, v[162:163]
	s_add_i32 m0, s51, 0x2000
	s_nop 0
	global_load_lds_dwordx4 v[218:219], off
	v_lshl_add_u64 v[218:219], s[30:31], 0, v[168:169]
	s_mov_b32 m0, s14
	s_nop 0
	global_load_lds_dwordx4 v[218:219], off
	s_mov_b32 m0, s15
	s_nop 0
	global_load_lds_dwordx4 v[220:221], off
	s_waitcnt vmcnt(8)
	s_waitcnt lgkmcnt(0)
	s_barrier
	v_mfma_f32_16x16x32_bf16 v[62:65], v[130:133], v[174:177], v[62:65]
	v_mfma_f32_16x16x32_bf16 v[62:65], v[134:137], v[180:183], v[62:65]
	v_mfma_f32_16x16x32_bf16 v[58:61], v[138:141], v[174:177], v[58:61]
	v_mfma_f32_16x16x32_bf16 v[58:61], v[142:145], v[180:183], v[58:61]
	v_mfma_f32_16x16x32_bf16 v[46:49], v[130:133], v[184:187], v[46:49]
	v_mfma_f32_16x16x32_bf16 v[46:49], v[134:137], v[188:191], v[46:49]
	v_mfma_f32_16x16x32_bf16 v[42:45], v[138:141], v[184:187], v[42:45]
	v_mfma_f32_16x16x32_bf16 v[42:45], v[142:145], v[188:191], v[42:45]
	v_mfma_f32_16x16x32_bf16 v[30:33], v[130:133], v[200:203], v[30:33]
	v_mfma_f32_16x16x32_bf16 v[30:33], v[134:137], v[204:207], v[30:33]
	v_mfma_f32_16x16x32_bf16 v[26:29], v[138:141], v[200:203], v[26:29]
	v_mfma_f32_16x16x32_bf16 v[26:29], v[142:145], v[204:207], v[26:29]
	v_mfma_f32_16x16x32_bf16 v[14:17], v[130:133], v[208:211], v[14:17]
	v_mfma_f32_16x16x32_bf16 v[14:17], v[134:137], v[212:215], v[14:17]
	v_mfma_f32_16x16x32_bf16 v[10:13], v[138:141], v[208:211], v[10:13]
	v_mfma_f32_16x16x32_bf16 v[10:13], v[142:145], v[212:215], v[10:13]
	v_mfma_f32_16x16x32_bf16 v[54:57], v[146:149], v[174:177], v[54:57]
	v_mfma_f32_16x16x32_bf16 v[54:57], v[150:153], v[180:183], v[54:57]
	v_mfma_f32_16x16x32_bf16 v[50:53], v[154:157], v[174:177], v[50:53]
	v_mfma_f32_16x16x32_bf16 v[50:53], v[158:161], v[180:183], v[50:53]
	v_mfma_f32_16x16x32_bf16 v[38:41], v[146:149], v[184:187], v[38:41]
	v_mfma_f32_16x16x32_bf16 v[38:41], v[150:153], v[188:191], v[38:41]
	v_mfma_f32_16x16x32_bf16 v[34:37], v[154:157], v[184:187], v[34:37]
	v_mfma_f32_16x16x32_bf16 v[34:37], v[158:161], v[188:191], v[34:37]
	v_mfma_f32_16x16x32_bf16 v[22:25], v[146:149], v[200:203], v[22:25]
	v_mfma_f32_16x16x32_bf16 v[22:25], v[150:153], v[204:207], v[22:25]
	v_mfma_f32_16x16x32_bf16 v[18:21], v[154:157], v[200:203], v[18:21]
	v_mfma_f32_16x16x32_bf16 v[18:21], v[158:161], v[204:207], v[18:21]
	v_mfma_f32_16x16x32_bf16 v[6:9], v[146:149], v[208:211], v[6:9]
	v_mfma_f32_16x16x32_bf16 v[6:9], v[150:153], v[212:215], v[6:9]
	v_mfma_f32_16x16x32_bf16 v[2:5], v[154:157], v[208:211], v[2:5]
	v_mfma_f32_16x16x32_bf16 v[2:5], v[158:161], v[212:215], v[2:5]
	s_barrier
	s_add_i32 s51, 0, 0x18000
	v_add_u32_e32 v0, s51, v179
	s_add_i32 s77, 0, 0x1c000
	ds_read_b128 v[130:133], v0
	ds_read_b128 v[134:137], v0 offset:1024
	ds_read_b128 v[138:141], v0 offset:2048
	ds_read_b128 v[142:145], v0 offset:3072
	v_add_u32_e32 v0, s77, v179
	ds_read_b128 v[146:149], v0
	ds_read_b128 v[150:153], v0 offset:1024
	ds_read_b128 v[154:157], v0 offset:2048
	ds_read_b128 v[158:161], v0 offset:3072
	s_add_u32 s30, s30, 0x100000
	s_addc_u32 s31, s31, 0
	s_mov_b32 m0, s52
	v_lshl_add_u64 v[222:223], s[30:31], 0, v[168:169]
	ds_read_b128 v[174:177], v192 offset:32768
	ds_read_b128 v[180:183], v192 offset:33792
	ds_read_b128 v[184:187], v192 offset:34816
	ds_read_b128 v[188:191], v192 offset:35840
	ds_read_b128 v[200:203], v192 offset:36864
	ds_read_b128 v[204:207], v192 offset:37888
	ds_read_b128 v[208:211], v192 offset:38912
	ds_read_b128 v[212:215], v192 offset:39936
	global_load_lds_dwordx4 v[222:223], off
	v_lshl_add_u64 v[222:223], s[30:31], 0, v[164:165]
	s_mov_b32 m0, s53
	s_nop 0
	global_load_lds_dwordx4 v[222:223], off
	s_waitcnt vmcnt(8)
	s_waitcnt lgkmcnt(0)
	s_barrier
	v_mfma_f32_16x16x32_bf16 v[126:129], v[130:133], v[174:177], v[126:129]
	v_mfma_f32_16x16x32_bf16 v[126:129], v[134:137], v[180:183], v[126:129]
	v_mfma_f32_16x16x32_bf16 v[122:125], v[138:141], v[174:177], v[122:125]
	v_mfma_f32_16x16x32_bf16 v[122:125], v[142:145], v[180:183], v[122:125]
	v_mfma_f32_16x16x32_bf16 v[110:113], v[130:133], v[184:187], v[110:113]
	v_mfma_f32_16x16x32_bf16 v[110:113], v[134:137], v[188:191], v[110:113]
	v_mfma_f32_16x16x32_bf16 v[106:109], v[138:141], v[184:187], v[106:109]
	v_mfma_f32_16x16x32_bf16 v[106:109], v[142:145], v[188:191], v[106:109]
	v_mfma_f32_16x16x32_bf16 v[94:97], v[130:133], v[200:203], v[94:97]
	v_mfma_f32_16x16x32_bf16 v[94:97], v[134:137], v[204:207], v[94:97]
	v_mfma_f32_16x16x32_bf16 v[90:93], v[138:141], v[200:203], v[90:93]
	v_mfma_f32_16x16x32_bf16 v[90:93], v[142:145], v[204:207], v[90:93]
	v_mfma_f32_16x16x32_bf16 v[78:81], v[130:133], v[208:211], v[78:81]
	v_mfma_f32_16x16x32_bf16 v[78:81], v[134:137], v[212:215], v[78:81]
	v_mfma_f32_16x16x32_bf16 v[74:77], v[138:141], v[208:211], v[74:77]
	v_mfma_f32_16x16x32_bf16 v[74:77], v[142:145], v[212:215], v[74:77]
	v_mfma_f32_16x16x32_bf16 v[118:121], v[146:149], v[174:177], v[118:121]
	v_mfma_f32_16x16x32_bf16 v[118:121], v[150:153], v[180:183], v[118:121]
	v_mfma_f32_16x16x32_bf16 v[114:117], v[154:157], v[174:177], v[114:117]
	v_mfma_f32_16x16x32_bf16 v[114:117], v[158:161], v[180:183], v[114:117]
	v_mfma_f32_16x16x32_bf16 v[102:105], v[146:149], v[184:187], v[102:105]
	v_mfma_f32_16x16x32_bf16 v[102:105], v[150:153], v[188:191], v[102:105]
	v_mfma_f32_16x16x32_bf16 v[98:101], v[154:157], v[184:187], v[98:101]
	v_mfma_f32_16x16x32_bf16 v[98:101], v[158:161], v[188:191], v[98:101]
	v_mfma_f32_16x16x32_bf16 v[86:89], v[146:149], v[200:203], v[86:89]
	v_mfma_f32_16x16x32_bf16 v[86:89], v[150:153], v[204:207], v[86:89]
	v_mfma_f32_16x16x32_bf16 v[82:85], v[154:157], v[200:203], v[82:85]
	v_mfma_f32_16x16x32_bf16 v[82:85], v[158:161], v[204:207], v[82:85]
	v_mfma_f32_16x16x32_bf16 v[70:73], v[146:149], v[208:211], v[70:73]
	v_mfma_f32_16x16x32_bf16 v[70:73], v[150:153], v[212:215], v[70:73]
	v_mfma_f32_16x16x32_bf16 v[66:69], v[154:157], v[208:211], v[66:69]
	v_mfma_f32_16x16x32_bf16 v[66:69], v[158:161], v[212:215], v[66:69]
	s_barrier
	s_add_i32 s30, s51, s9
	v_lshl_add_u64 v[194:195], v[194:195], 0, s[12:13]
	s_mov_b32 m0, s30
	ds_read_b128 v[174:177], v192 offset:49152
	ds_read_b128 v[180:183], v192 offset:50176
	ds_read_b128 v[184:187], v192 offset:51200
	ds_read_b128 v[188:191], v192 offset:52224
	ds_read_b128 v[200:203], v192 offset:53248
	ds_read_b128 v[204:207], v192 offset:54272
	ds_read_b128 v[208:211], v192 offset:55296
	ds_read_b128 v[212:215], v192 offset:56320
	global_load_lds_dwordx4 v[194:195], off
	s_add_i32 m0, s30, 0x2000
	s_add_u32 s28, s28, 0x100080
	v_lshl_add_u64 v[194:195], v[216:217], 0, s[12:13]
	s_addc_u32 s29, s29, 0
	s_add_i32 s30, s77, s9
	global_load_lds_dwordx4 v[194:195], off
	v_lshl_add_u64 v[194:195], s[28:29], 0, v[166:167]
	s_mov_b32 m0, s30
	s_nop 0
	global_load_lds_dwordx4 v[194:195], off
	v_lshl_add_u64 v[194:195], s[28:29], 0, v[162:163]
	s_add_i32 m0, s30, 0x2000
	s_nop 0
	global_load_lds_dwordx4 v[194:195], off
	v_lshl_add_u64 v[194:195], v[218:219], 0, s[12:13]
	s_mov_b32 m0, s54
	s_nop 0
	global_load_lds_dwordx4 v[194:195], off
	v_lshl_add_u64 v[194:195], v[220:221], 0, s[12:13]
	s_mov_b32 m0, s55
	s_nop 0
	global_load_lds_dwordx4 v[194:195], off
	s_waitcnt vmcnt(8)
	s_waitcnt lgkmcnt(0)
	s_barrier
	v_mfma_f32_16x16x32_bf16 v[62:65], v[130:133], v[174:177], v[62:65]
	v_mfma_f32_16x16x32_bf16 v[62:65], v[134:137], v[180:183], v[62:65]
	v_mfma_f32_16x16x32_bf16 v[58:61], v[138:141], v[174:177], v[58:61]
	v_mfma_f32_16x16x32_bf16 v[58:61], v[142:145], v[180:183], v[58:61]
	v_mfma_f32_16x16x32_bf16 v[46:49], v[130:133], v[184:187], v[46:49]
	v_mfma_f32_16x16x32_bf16 v[46:49], v[134:137], v[188:191], v[46:49]
	v_mfma_f32_16x16x32_bf16 v[42:45], v[138:141], v[184:187], v[42:45]
	v_mfma_f32_16x16x32_bf16 v[42:45], v[142:145], v[188:191], v[42:45]
	v_mfma_f32_16x16x32_bf16 v[30:33], v[130:133], v[200:203], v[30:33]
	v_mfma_f32_16x16x32_bf16 v[30:33], v[134:137], v[204:207], v[30:33]
	v_mfma_f32_16x16x32_bf16 v[26:29], v[138:141], v[200:203], v[26:29]
	v_mfma_f32_16x16x32_bf16 v[26:29], v[142:145], v[204:207], v[26:29]
	v_mfma_f32_16x16x32_bf16 v[14:17], v[130:133], v[208:211], v[14:17]
	v_mfma_f32_16x16x32_bf16 v[14:17], v[134:137], v[212:215], v[14:17]
	v_mfma_f32_16x16x32_bf16 v[10:13], v[138:141], v[208:211], v[10:13]
	v_mfma_f32_16x16x32_bf16 v[10:13], v[142:145], v[212:215], v[10:13]
	v_mfma_f32_16x16x32_bf16 v[54:57], v[146:149], v[174:177], v[54:57]
	v_mfma_f32_16x16x32_bf16 v[54:57], v[150:153], v[180:183], v[54:57]
	v_mfma_f32_16x16x32_bf16 v[50:53], v[154:157], v[174:177], v[50:53]
	v_mfma_f32_16x16x32_bf16 v[50:53], v[158:161], v[180:183], v[50:53]
	v_mfma_f32_16x16x32_bf16 v[38:41], v[146:149], v[184:187], v[38:41]
	v_mfma_f32_16x16x32_bf16 v[38:41], v[150:153], v[188:191], v[38:41]
	v_mfma_f32_16x16x32_bf16 v[34:37], v[154:157], v[184:187], v[34:37]
	v_mfma_f32_16x16x32_bf16 v[34:37], v[158:161], v[188:191], v[34:37]
	v_mfma_f32_16x16x32_bf16 v[22:25], v[146:149], v[200:203], v[22:25]
	v_mfma_f32_16x16x32_bf16 v[22:25], v[150:153], v[204:207], v[22:25]
	v_mfma_f32_16x16x32_bf16 v[18:21], v[154:157], v[200:203], v[18:21]
	v_mfma_f32_16x16x32_bf16 v[18:21], v[158:161], v[204:207], v[18:21]
	v_mfma_f32_16x16x32_bf16 v[6:9], v[146:149], v[208:211], v[6:9]
	v_mfma_f32_16x16x32_bf16 v[6:9], v[150:153], v[212:215], v[6:9]
	v_mfma_f32_16x16x32_bf16 v[2:5], v[154:157], v[208:211], v[2:5]
	v_mfma_f32_16x16x32_bf16 v[2:5], v[158:161], v[212:215], v[2:5]
	s_barrier
	s_add_i32 s50, s50, 2
	s_add_u32 s0, s0, 0x100
	s_addc_u32 s1, s1, 0
	s_add_u32 s41, s41, 0x100
	s_addc_u32 s43, s43, 0
	s_cmp_gt_u32 s50, 61
	s_cbranch_scc0 .LBB0_230
	s_and_b64 vcc, exec, s[22:23]
	s_cbranch_vccz .LBB0_233
	s_barrier

.LBB0_300:
	s_add_u32 s100, s0, 0xfff80000
	s_addc_u32 s101, s1, -1
	s_add_u32 s28, s0, 0xfff80080
	s_addc_u32 s29, s1, -1
	s_add_i32 s42, 0, 0x10000
	s_cmp_eq_u32 s41, 28
	s_cselect_b32 s31, s18, s29
	s_cselect_b32 s30, s19, s28
	v_add_u32_e32 v0, s42, v199
	s_cselect_b32 s29, s27, s40
	s_cselect_b32 s28, s34, s35
	s_add_i32 s49, 0, 0x14000
	ds_read_b128 v[2:5], v0
	ds_read_b128 v[6:9], v0 offset:1024
	ds_read_b128 v[10:13], v0 offset:2048
	ds_read_b128 v[14:17], v0 offset:3072
	v_add_u32_e32 v0, s49, v199
	ds_read_b128 v[146:149], v0
	ds_read_b128 v[150:153], v0 offset:1024
	ds_read_b128 v[154:157], v0 offset:2048
	ds_read_b128 v[158:161], v0 offset:3072
	v_lshl_add_u64 v[194:195], s[100:101], 0, v[162:163]
	s_mov_b32 m0, s15
	ds_read_b128 v[174:177], v250
	ds_read_b128 v[178:181], v250 offset:1024
	ds_read_b128 v[182:185], v250 offset:2048
	ds_read_b128 v[186:189], v250 offset:3072
	ds_read_b128 v[190:193], v250 offset:4096
	ds_read_b128 v[200:203], v250 offset:5120
	ds_read_b128 v[204:207], v250 offset:6144
	ds_read_b128 v[208:211], v250 offset:7168
	global_load_lds_dwordx4 v[194:195], off
	v_lshl_add_u64 v[194:195], s[100:101], 0, v[166:167]
	s_mov_b32 m0, s88
	s_nop 0
	global_load_lds_dwordx4 v[194:195], off
	v_lshl_add_u64 v[194:195], s[0:1], 0, v[170:171]
	s_add_i32 m0, s21, 0xc000
	s_nop 0
	global_load_lds_dwordx4 v[194:195], off
	v_lshl_add_u64 v[194:195], s[0:1], 0, v[172:173]
	s_add_i32 m0, s21, 0xe000
	s_nop 0
	global_load_lds_dwordx4 v[194:195], off
	s_waitcnt vmcnt(8)
	s_waitcnt lgkmcnt(0)
	s_barrier
	v_mfma_i32_16x16x64_i8 v[142:145], v[2:5], v[174:177], v[142:145]
	v_mfma_i32_16x16x64_i8 v[142:145], v[6:9], v[178:181], v[142:145]
	v_mfma_i32_16x16x64_i8 v[138:141], v[10:13], v[174:177], v[138:141]
	v_mfma_i32_16x16x64_i8 v[138:141], v[14:17], v[178:181], v[138:141]
	v_mfma_i32_16x16x64_i8 v[134:137], v[2:5], v[182:185], v[134:137]
	v_mfma_i32_16x16x64_i8 v[134:137], v[6:9], v[186:189], v[134:137]
	v_mfma_i32_16x16x64_i8 v[130:133], v[10:13], v[182:185], v[130:133]
	v_mfma_i32_16x16x64_i8 v[130:133], v[14:17], v[186:189], v[130:133]
	v_mfma_i32_16x16x64_i8 v[122:125], v[2:5], v[190:193], v[122:125]
	v_mfma_i32_16x16x64_i8 v[122:125], v[6:9], v[200:203], v[122:125]
	v_mfma_i32_16x16x64_i8 v[114:117], v[10:13], v[190:193], v[114:117]
	v_mfma_i32_16x16x64_i8 v[114:117], v[14:17], v[200:203], v[114:117]
	v_mfma_i32_16x16x64_i8 v[106:109], v[2:5], v[204:207], v[106:109]
	v_mfma_i32_16x16x64_i8 v[106:109], v[6:9], v[208:211], v[106:109]
	v_mfma_i32_16x16x64_i8 v[98:101], v[10:13], v[204:207], v[98:101]
	v_mfma_i32_16x16x64_i8 v[98:101], v[14:17], v[208:211], v[98:101]
	v_mfma_i32_16x16x64_i8 v[126:129], v[146:149], v[174:177], v[126:129]
	v_mfma_i32_16x16x64_i8 v[126:129], v[150:153], v[178:181], v[126:129]
	v_mfma_i32_16x16x64_i8 v[118:121], v[154:157], v[174:177], v[118:121]
	v_mfma_i32_16x16x64_i8 v[118:121], v[158:161], v[178:181], v[118:121]
	v_mfma_i32_16x16x64_i8 v[110:113], v[146:149], v[182:185], v[110:113]
	v_mfma_i32_16x16x64_i8 v[110:113], v[150:153], v[186:189], v[110:113]
	v_mfma_i32_16x16x64_i8 v[102:105], v[154:157], v[182:185], v[102:105]
	v_mfma_i32_16x16x64_i8 v[102:105], v[158:161], v[186:189], v[102:105]
	v_mfma_i32_16x16x64_i8 v[94:97], v[146:149], v[190:193], v[94:97]
	v_mfma_i32_16x16x64_i8 v[94:97], v[150:153], v[200:203], v[94:97]
	v_mfma_i32_16x16x64_i8 v[90:93], v[154:157], v[190:193], v[90:93]
	v_mfma_i32_16x16x64_i8 v[90:93], v[158:161], v[200:203], v[90:93]
	v_mfma_i32_16x16x64_i8 v[86:89], v[146:149], v[204:207], v[86:89]
	v_mfma_i32_16x16x64_i8 v[86:89], v[150:153], v[208:211], v[86:89]
	v_mfma_i32_16x16x64_i8 v[82:85], v[154:157], v[204:207], v[82:85]
	v_mfma_i32_16x16x64_i8 v[82:85], v[158:161], v[208:211], v[82:85]
	s_barrier
	s_add_i32 s42, s42, s81
	v_lshl_add_u64 v[194:195], s[28:29], 0, v[164:165]
	s_mov_b32 m0, s42
	ds_read_b128 v[174:177], v250 offset:16384
	ds_read_b128 v[178:181], v250 offset:17408
	ds_read_b128 v[182:185], v250 offset:18432
	ds_read_b128 v[186:189], v250 offset:19456
	ds_read_b128 v[190:193], v250 offset:20480
	ds_read_b128 v[200:203], v250 offset:21504
	ds_read_b128 v[204:207], v250 offset:22528
	ds_read_b128 v[208:211], v250 offset:23552
	global_load_lds_dwordx4 v[194:195], off
	s_add_i32 m0, s42, 0x2000
	s_add_u32 s42, s28, 0x80000
	v_lshl_add_u64 v[212:213], s[28:29], 0, v[168:169]
	s_addc_u32 s43, s29, 0
	s_add_i32 s49, s49, s81
	global_load_lds_dwordx4 v[212:213], off
	v_lshl_add_u64 v[214:215], s[42:43], 0, v[164:165]
	s_mov_b32 m0, s49
	v_lshl_add_u64 v[216:217], s[30:31], 0, v[166:167]
	global_load_lds_dwordx4 v[214:215], off
	v_lshl_add_u64 v[214:215], s[42:43], 0, v[168:169]
	s_add_i32 m0, s49, 0x2000
	s_nop 0
	global_load_lds_dwordx4 v[214:215], off
	v_lshl_add_u64 v[214:215], s[30:31], 0, v[162:163]
	s_waitcnt vmcnt(6)
	s_waitcnt lgkmcnt(0)
	s_barrier
	v_mfma_i32_16x16x64_i8 v[78:81], v[2:5], v[174:177], v[78:81]
	v_mfma_i32_16x16x64_i8 v[78:81], v[6:9], v[178:181], v[78:81]
	v_mfma_i32_16x16x64_i8 v[74:77], v[10:13], v[174:177], v[74:77]
	v_mfma_i32_16x16x64_i8 v[74:77], v[14:17], v[178:181], v[74:77]
	v_mfma_i32_16x16x64_i8 v[70:73], v[2:5], v[182:185], v[70:73]
	v_mfma_i32_16x16x64_i8 v[70:73], v[6:9], v[186:189], v[70:73]
	v_mfma_i32_16x16x64_i8 v[66:69], v[10:13], v[182:185], v[66:69]
	v_mfma_i32_16x16x64_i8 v[66:69], v[14:17], v[186:189], v[66:69]
	v_mfma_i32_16x16x64_i8 v[54:57], v[2:5], v[190:193], v[54:57]
	v_mfma_i32_16x16x64_i8 v[54:57], v[6:9], v[200:203], v[54:57]
	v_mfma_i32_16x16x64_i8 v[50:53], v[10:13], v[190:193], v[50:53]
	v_mfma_i32_16x16x64_i8 v[50:53], v[14:17], v[200:203], v[50:53]
	v_mfma_i32_16x16x64_i8 v[2:5], v[2:5], v[204:207], v[38:41]
	v_mfma_i32_16x16x64_i8 v[2:5], v[6:9], v[208:211], v[2:5]
	v_mfma_i32_16x16x64_i8 v[6:9], v[10:13], v[204:207], v[34:37]
	v_mfma_i32_16x16x64_i8 v[6:9], v[14:17], v[208:211], v[6:9]
	v_mfma_i32_16x16x64_i8 v[34:37], v[146:149], v[182:185], v[46:49]
	v_mfma_i32_16x16x64_i8 v[46:49], v[150:153], v[186:189], v[34:37]
	v_mfma_i32_16x16x64_i8 v[34:37], v[154:157], v[182:185], v[42:45]
	v_mfma_i32_16x16x64_i8 v[42:45], v[158:161], v[186:189], v[34:37]
	v_mfma_i32_16x16x64_i8 v[30:33], v[146:149], v[190:193], v[30:33]
	v_mfma_i32_16x16x64_i8 v[30:33], v[150:153], v[200:203], v[30:33]
	v_mfma_i32_16x16x64_i8 v[26:29], v[154:157], v[190:193], v[26:29]
	v_mfma_i32_16x16x64_i8 v[26:29], v[158:161], v[200:203], v[26:29]
	v_mfma_i32_16x16x64_i8 v[22:25], v[146:149], v[204:207], v[22:25]
	v_mfma_i32_16x16x64_i8 v[22:25], v[150:153], v[208:211], v[22:25]
	v_mfma_i32_16x16x64_i8 v[18:21], v[154:157], v[204:207], v[18:21]
	v_mfma_i32_16x16x64_i8 v[18:21], v[158:161], v[208:211], v[18:21]
	v_mfma_i32_16x16x64_i8 v[10:13], v[146:149], v[174:177], v[62:65]
	v_mfma_i32_16x16x64_i8 v[10:13], v[150:153], v[178:181], v[10:13]
	v_mfma_i32_16x16x64_i8 v[14:17], v[154:157], v[174:177], v[58:61]
	v_mfma_i32_16x16x64_i8 v[14:17], v[158:161], v[178:181], v[14:17]
	s_barrier
	s_add_i32 s42, 0, 0x18000
	v_add_u32_e32 v0, s42, v199
	s_add_i32 s43, 0, 0x1c000
	ds_read_b128 v[34:37], v0
	ds_read_b128 v[38:41], v0 offset:1024
	ds_read_b128 v[58:61], v0 offset:2048
	ds_read_b128 v[62:65], v0 offset:3072
	v_add_u32_e32 v0, s43, v199
	ds_read_b128 v[146:149], v0
	ds_read_b128 v[150:153], v0 offset:1024
	ds_read_b128 v[154:157], v0 offset:2048
	ds_read_b128 v[158:161], v0 offset:3072
	s_add_u32 s30, s30, 0x80000
	s_addc_u32 s31, s31, 0
	s_mov_b32 m0, s21
	v_lshl_add_u64 v[218:219], s[30:31], 0, v[162:163]
	ds_read_b128 v[174:177], v250 offset:32768
	ds_read_b128 v[178:181], v250 offset:33792
	ds_read_b128 v[182:185], v250 offset:34816
	ds_read_b128 v[186:189], v250 offset:35840
	ds_read_b128 v[190:193], v250 offset:36864
	ds_read_b128 v[200:203], v250 offset:37888
	ds_read_b128 v[204:207], v250 offset:38912
	ds_read_b128 v[208:211], v250 offset:39936
	global_load_lds_dwordx4 v[214:215], off
	s_mov_b32 m0, s57
	s_nop 0
	global_load_lds_dwordx4 v[216:217], off
	s_mov_b32 m0, s73
	s_nop 0
	global_load_lds_dwordx4 v[218:219], off
	v_lshl_add_u64 v[218:219], s[30:31], 0, v[166:167]
	s_mov_b32 m0, s76
	s_nop 0
	global_load_lds_dwordx4 v[218:219], off
	s_waitcnt vmcnt(8)
	s_waitcnt lgkmcnt(0)
	s_barrier
	v_mfma_i32_16x16x64_i8 v[142:145], v[34:37], v[174:177], v[142:145]
	v_mfma_i32_16x16x64_i8 v[142:145], v[38:41], v[178:181], v[142:145]
	v_mfma_i32_16x16x64_i8 v[138:141], v[58:61], v[174:177], v[138:141]
	v_mfma_i32_16x16x64_i8 v[138:141], v[62:65], v[178:181], v[138:141]
	v_mfma_i32_16x16x64_i8 v[134:137], v[34:37], v[182:185], v[134:137]
	v_mfma_i32_16x16x64_i8 v[134:137], v[38:41], v[186:189], v[134:137]
	v_mfma_i32_16x16x64_i8 v[130:133], v[58:61], v[182:185], v[130:133]
	v_mfma_i32_16x16x64_i8 v[130:133], v[62:65], v[186:189], v[130:133]
	v_mfma_i32_16x16x64_i8 v[122:125], v[34:37], v[190:193], v[122:125]
	v_mfma_i32_16x16x64_i8 v[122:125], v[38:41], v[200:203], v[122:125]
	v_mfma_i32_16x16x64_i8 v[114:117], v[58:61], v[190:193], v[114:117]
	v_mfma_i32_16x16x64_i8 v[114:117], v[62:65], v[200:203], v[114:117]
	v_mfma_i32_16x16x64_i8 v[106:109], v[34:37], v[204:207], v[106:109]
	v_mfma_i32_16x16x64_i8 v[106:109], v[38:41], v[208:211], v[106:109]
	v_mfma_i32_16x16x64_i8 v[98:101], v[58:61], v[204:207], v[98:101]
	v_mfma_i32_16x16x64_i8 v[98:101], v[62:65], v[208:211], v[98:101]
	v_mfma_i32_16x16x64_i8 v[126:129], v[146:149], v[174:177], v[126:129]
	v_mfma_i32_16x16x64_i8 v[126:129], v[150:153], v[178:181], v[126:129]
	v_mfma_i32_16x16x64_i8 v[118:121], v[154:157], v[174:177], v[118:121]
	v_mfma_i32_16x16x64_i8 v[118:121], v[158:161], v[178:181], v[118:121]
	v_mfma_i32_16x16x64_i8 v[110:113], v[146:149], v[182:185], v[110:113]
	v_mfma_i32_16x16x64_i8 v[110:113], v[150:153], v[186:189], v[110:113]
	v_mfma_i32_16x16x64_i8 v[102:105], v[154:157], v[182:185], v[102:105]
	v_mfma_i32_16x16x64_i8 v[102:105], v[158:161], v[186:189], v[102:105]
	v_mfma_i32_16x16x64_i8 v[94:97], v[146:149], v[190:193], v[94:97]
	v_mfma_i32_16x16x64_i8 v[94:97], v[150:153], v[200:203], v[94:97]
	v_mfma_i32_16x16x64_i8 v[90:93], v[154:157], v[190:193], v[90:93]
	v_mfma_i32_16x16x64_i8 v[90:93], v[158:161], v[200:203], v[90:93]
	v_mfma_i32_16x16x64_i8 v[86:89], v[146:149], v[204:207], v[86:89]
	v_mfma_i32_16x16x64_i8 v[86:89], v[150:153], v[208:211], v[86:89]
	v_mfma_i32_16x16x64_i8 v[82:85], v[154:157], v[204:207], v[82:85]
	v_mfma_i32_16x16x64_i8 v[82:85], v[158:161], v[208:211], v[82:85]
	s_barrier
	s_add_i32 s30, s42, s81
	v_lshl_add_u64 v[194:195], v[194:195], 0, s[12:13]
	s_mov_b32 m0, s30
	ds_read_b128 v[174:177], v250 offset:49152
	ds_read_b128 v[178:181], v250 offset:50176
	ds_read_b128 v[182:185], v250 offset:51200
	ds_read_b128 v[186:189], v250 offset:52224
	ds_read_b128 v[190:193], v250 offset:53248
	ds_read_b128 v[200:203], v250 offset:54272
	ds_read_b128 v[204:207], v250 offset:55296
	ds_read_b128 v[208:211], v250 offset:56320
	global_load_lds_dwordx4 v[194:195], off
	s_add_i32 m0, s30, 0x2000
	s_add_u32 s28, s28, 0x80080
	v_lshl_add_u64 v[194:195], v[212:213], 0, s[12:13]
	s_addc_u32 s29, s29, 0
	s_add_i32 s30, s43, s81
	global_load_lds_dwordx4 v[194:195], off
	v_lshl_add_u64 v[194:195], s[28:29], 0, v[164:165]
	s_mov_b32 m0, s30
	s_nop 0
	global_load_lds_dwordx4 v[194:195], off
	v_lshl_add_u64 v[194:195], s[28:29], 0, v[168:169]
	s_add_i32 m0, s30, 0x2000
	s_nop 0
	global_load_lds_dwordx4 v[194:195], off
	s_waitcnt vmcnt(6)
	s_waitcnt lgkmcnt(0)
	s_barrier
	v_mfma_i32_16x16x64_i8 v[78:81], v[34:37], v[174:177], v[78:81]
	v_mfma_i32_16x16x64_i8 v[78:81], v[38:41], v[178:181], v[78:81]
	v_mfma_i32_16x16x64_i8 v[70:73], v[34:37], v[182:185], v[70:73]
	v_mfma_i32_16x16x64_i8 v[70:73], v[38:41], v[186:189], v[70:73]
	v_mfma_i32_16x16x64_i8 v[54:57], v[34:37], v[190:193], v[54:57]
	v_mfma_i32_16x16x64_i8 v[54:57], v[38:41], v[200:203], v[54:57]
	v_mfma_i32_16x16x64_i8 v[2:5], v[34:37], v[204:207], v[2:5]
	v_mfma_i32_16x16x64_i8 v[38:41], v[38:41], v[208:211], v[2:5]
	v_mfma_i32_16x16x64_i8 v[74:77], v[58:61], v[174:177], v[74:77]
	v_mfma_i32_16x16x64_i8 v[74:77], v[62:65], v[178:181], v[74:77]
	v_mfma_i32_16x16x64_i8 v[66:69], v[58:61], v[182:185], v[66:69]
	v_mfma_i32_16x16x64_i8 v[66:69], v[62:65], v[186:189], v[66:69]
	v_mfma_i32_16x16x64_i8 v[50:53], v[58:61], v[190:193], v[50:53]
	v_mfma_i32_16x16x64_i8 v[50:53], v[62:65], v[200:203], v[50:53]
	v_mfma_i32_16x16x64_i8 v[2:5], v[58:61], v[204:207], v[6:9]
	v_mfma_i32_16x16x64_i8 v[34:37], v[62:65], v[208:211], v[2:5]
	v_mfma_i32_16x16x64_i8 v[2:5], v[146:149], v[174:177], v[10:13]
	v_mfma_i32_16x16x64_i8 v[62:65], v[150:153], v[178:181], v[2:5]
	v_mfma_i32_16x16x64_i8 v[2:5], v[154:157], v[174:177], v[14:17]
	v_mfma_i32_16x16x64_i8 v[58:61], v[158:161], v[178:181], v[2:5]
	v_mfma_i32_16x16x64_i8 v[2:5], v[146:149], v[182:185], v[46:49]
	v_mfma_i32_16x16x64_i8 v[46:49], v[150:153], v[186:189], v[2:5]
	v_mfma_i32_16x16x64_i8 v[2:5], v[154:157], v[182:185], v[42:45]
	v_mfma_i32_16x16x64_i8 v[42:45], v[158:161], v[186:189], v[2:5]
	v_mfma_i32_16x16x64_i8 v[2:5], v[146:149], v[190:193], v[30:33]
	v_mfma_i32_16x16x64_i8 v[30:33], v[150:153], v[200:203], v[2:5]
	v_mfma_i32_16x16x64_i8 v[2:5], v[154:157], v[190:193], v[26:29]
	v_mfma_i32_16x16x64_i8 v[26:29], v[158:161], v[200:203], v[2:5]
	v_mfma_i32_16x16x64_i8 v[2:5], v[146:149], v[204:207], v[22:25]
	v_mfma_i32_16x16x64_i8 v[22:25], v[150:153], v[208:211], v[2:5]
	v_mfma_i32_16x16x64_i8 v[2:5], v[154:157], v[204:207], v[18:21]
	v_mfma_i32_16x16x64_i8 v[18:21], v[158:161], v[208:211], v[2:5]
	s_barrier
	s_add_i32 s41, s41, 2
	s_add_u32 s0, s0, 0x100
	s_addc_u32 s1, s1, 0
	s_add_u32 s35, s35, 0x100
	s_addc_u32 s40, s40, 0
	s_cmp_gt_u32 s41, 29
	s_cbranch_scc0 .LBB0_300
	s_and_b64 vcc, exec, s[52:53]
	s_cbranch_vccz .LBB0_303
	s_barrier

.LBB0_577:
	s_add_u32 s34, s30, 0xfff80080
	s_addc_u32 s35, s31, -1
	s_add_i32 s66, 0, 0x10000
	s_cmp_eq_u32 s57, 28
	s_cselect_b32 s43, s19, s35
	s_cselect_b32 s42, s23, s34
	v_add_u32_e32 v0, s66, v228
	s_cselect_b32 s35, s25, s56
	s_cselect_b32 s34, s54, s55
	s_add_i32 s73, 0, 0x14000
	ds_read_b128 v[132:135], v0
	ds_read_b128 v[136:139], v0 offset:1024
	ds_read_b128 v[140:143], v0 offset:2048
	ds_read_b128 v[144:147], v0 offset:3072
	v_add_u32_e32 v0, s73, v228
	ds_read_b128 v[148:151], v0
	ds_read_b128 v[152:155], v0 offset:1024
	ds_read_b128 v[156:159], v0 offset:2048
	ds_read_b128 v[160:163], v0 offset:3072
	v_lshl_add_u64 v[2:3], s[30:31], 0, v[208:209]
	s_add_i32 m0, s46, 0xc000
	ds_read_b128 v[164:167], v230
	ds_read_b128 v[168:171], v230 offset:1024
	ds_read_b128 v[172:175], v230 offset:2048
	ds_read_b128 v[176:179], v230 offset:3072
	ds_read_b128 v[180:183], v230 offset:4096
	ds_read_b128 v[184:187], v230 offset:5120
	ds_read_b128 v[188:191], v230 offset:6144
	ds_read_b128 v[192:195], v230 offset:7168
	global_load_lds_dwordx4 v[2:3], off
	v_lshl_add_u64 v[2:3], s[30:31], 0, v[210:211]
	s_add_i32 m0, s46, 0xe000
	s_nop 0
	global_load_lds_dwordx4 v[2:3], off
	s_waitcnt vmcnt(8)
	s_waitcnt lgkmcnt(0)
	s_barrier
	v_mfma_f32_16x16x32_bf16 v[128:131], v[132:135], v[164:167], v[128:131]
	v_mfma_f32_16x16x32_bf16 v[128:131], v[136:139], v[168:171], v[128:131]
	v_mfma_f32_16x16x32_bf16 v[124:127], v[140:143], v[164:167], v[124:127]
	v_mfma_f32_16x16x32_bf16 v[124:127], v[144:147], v[168:171], v[124:127]
	v_mfma_f32_16x16x32_bf16 v[120:123], v[132:135], v[172:175], v[120:123]
	v_mfma_f32_16x16x32_bf16 v[120:123], v[136:139], v[176:179], v[120:123]
	v_mfma_f32_16x16x32_bf16 v[116:119], v[140:143], v[172:175], v[116:119]
	v_mfma_f32_16x16x32_bf16 v[116:119], v[144:147], v[176:179], v[116:119]
	v_mfma_f32_16x16x32_bf16 v[112:115], v[132:135], v[180:183], v[112:115]
	v_mfma_f32_16x16x32_bf16 v[112:115], v[136:139], v[184:187], v[112:115]
	v_mfma_f32_16x16x32_bf16 v[108:111], v[140:143], v[180:183], v[108:111]
	v_mfma_f32_16x16x32_bf16 v[108:111], v[144:147], v[184:187], v[108:111]
	v_mfma_f32_16x16x32_bf16 v[104:107], v[132:135], v[188:191], v[104:107]
	v_mfma_f32_16x16x32_bf16 v[104:107], v[136:139], v[192:195], v[104:107]
	v_mfma_f32_16x16x32_bf16 v[100:103], v[140:143], v[188:191], v[100:103]
	v_mfma_f32_16x16x32_bf16 v[100:103], v[144:147], v[192:195], v[100:103]
	v_mfma_f32_16x16x32_bf16 v[96:99], v[148:151], v[164:167], v[96:99]
	v_mfma_f32_16x16x32_bf16 v[96:99], v[152:155], v[168:171], v[96:99]
	v_mfma_f32_16x16x32_bf16 v[92:95], v[156:159], v[164:167], v[92:95]
	v_mfma_f32_16x16x32_bf16 v[92:95], v[160:163], v[168:171], v[92:95]
	v_mfma_f32_16x16x32_bf16 v[88:91], v[148:151], v[172:175], v[88:91]
	v_mfma_f32_16x16x32_bf16 v[88:91], v[152:155], v[176:179], v[88:91]
	v_mfma_f32_16x16x32_bf16 v[84:87], v[156:159], v[172:175], v[84:87]
	v_mfma_f32_16x16x32_bf16 v[84:87], v[160:163], v[176:179], v[84:87]
	v_mfma_f32_16x16x32_bf16 v[80:83], v[148:151], v[180:183], v[80:83]
	v_mfma_f32_16x16x32_bf16 v[80:83], v[152:155], v[184:187], v[80:83]
	v_mfma_f32_16x16x32_bf16 v[76:79], v[156:159], v[180:183], v[76:79]
	v_mfma_f32_16x16x32_bf16 v[76:79], v[160:163], v[184:187], v[76:79]
	v_mfma_f32_16x16x32_bf16 v[72:75], v[148:151], v[188:191], v[72:75]
	v_mfma_f32_16x16x32_bf16 v[72:75], v[152:155], v[192:195], v[72:75]
	v_mfma_f32_16x16x32_bf16 v[68:71], v[156:159], v[188:191], v[68:71]
	v_mfma_f32_16x16x32_bf16 v[68:71], v[160:163], v[192:195], v[68:71]
	s_barrier
	s_add_i32 s66, s66, s15
	v_lshl_add_u64 v[212:213], s[34:35], 0, v[204:205]
	s_mov_b32 m0, s66
	ds_read_b128 v[164:167], v230 offset:16384
	ds_read_b128 v[168:171], v230 offset:17408
	ds_read_b128 v[172:175], v230 offset:18432
	ds_read_b128 v[176:179], v230 offset:19456
	ds_read_b128 v[180:183], v230 offset:20480
	ds_read_b128 v[184:187], v230 offset:21504
	ds_read_b128 v[188:191], v230 offset:22528
	ds_read_b128 v[192:195], v230 offset:23552
	global_load_lds_dwordx4 v[212:213], off
	s_add_i32 m0, s66, 0x2000
	s_add_u32 s66, s34, 0x80000
	v_lshl_add_u64 v[214:215], s[34:35], 0, v[200:201]
	s_addc_u32 s67, s35, 0
	s_add_i32 s73, s73, s15
	global_load_lds_dwordx4 v[214:215], off
	v_lshl_add_u64 v[2:3], s[66:67], 0, v[204:205]
	s_mov_b32 m0, s73
	v_lshl_add_u64 v[216:217], s[42:43], 0, v[206:207]
	global_load_lds_dwordx4 v[2:3], off
	v_lshl_add_u64 v[2:3], s[66:67], 0, v[200:201]
	s_add_i32 m0, s73, 0x2000
	v_lshl_add_u64 v[218:219], s[42:43], 0, v[202:203]
	global_load_lds_dwordx4 v[2:3], off
	s_mov_b32 m0, s46
	s_nop 0
	global_load_lds_dwordx4 v[216:217], off
	s_mov_b32 m0, s47
	s_nop 0
	global_load_lds_dwordx4 v[218:219], off
	s_waitcnt vmcnt(8)
	s_waitcnt lgkmcnt(0)
	s_barrier
	v_mfma_f32_16x16x32_bf16 v[64:67], v[132:135], v[164:167], v[64:67]
	v_mfma_f32_16x16x32_bf16 v[64:67], v[136:139], v[168:171], v[64:67]
	v_mfma_f32_16x16x32_bf16 v[60:63], v[140:143], v[164:167], v[60:63]
	v_mfma_f32_16x16x32_bf16 v[60:63], v[144:147], v[168:171], v[60:63]
	v_mfma_f32_16x16x32_bf16 v[56:59], v[132:135], v[172:175], v[56:59]
	v_mfma_f32_16x16x32_bf16 v[56:59], v[136:139], v[176:179], v[56:59]
	v_mfma_f32_16x16x32_bf16 v[52:55], v[140:143], v[172:175], v[52:55]
	v_mfma_f32_16x16x32_bf16 v[52:55], v[144:147], v[176:179], v[52:55]
	v_mfma_f32_16x16x32_bf16 v[48:51], v[132:135], v[180:183], v[48:51]
	v_mfma_f32_16x16x32_bf16 v[48:51], v[136:139], v[184:187], v[48:51]
	v_mfma_f32_16x16x32_bf16 v[44:47], v[140:143], v[180:183], v[44:47]
	v_mfma_f32_16x16x32_bf16 v[44:47], v[144:147], v[184:187], v[44:47]
	v_mfma_f32_16x16x32_bf16 v[40:43], v[132:135], v[188:191], v[40:43]
	v_mfma_f32_16x16x32_bf16 v[40:43], v[136:139], v[192:195], v[40:43]
	v_mfma_f32_16x16x32_bf16 v[36:39], v[140:143], v[188:191], v[36:39]
	v_mfma_f32_16x16x32_bf16 v[36:39], v[144:147], v[192:195], v[36:39]
	v_mfma_f32_16x16x32_bf16 v[32:35], v[148:151], v[164:167], v[32:35]
	v_mfma_f32_16x16x32_bf16 v[32:35], v[152:155], v[168:171], v[32:35]
	v_mfma_f32_16x16x32_bf16 v[28:31], v[156:159], v[164:167], v[28:31]
	v_mfma_f32_16x16x32_bf16 v[28:31], v[160:163], v[168:171], v[28:31]
	v_mfma_f32_16x16x32_bf16 v[24:27], v[148:151], v[172:175], v[24:27]
	v_mfma_f32_16x16x32_bf16 v[24:27], v[152:155], v[176:179], v[24:27]
	v_mfma_f32_16x16x32_bf16 v[20:23], v[156:159], v[172:175], v[20:23]
	v_mfma_f32_16x16x32_bf16 v[20:23], v[160:163], v[176:179], v[20:23]
	v_mfma_f32_16x16x32_bf16 v[16:19], v[148:151], v[180:183], v[16:19]
	v_mfma_f32_16x16x32_bf16 v[16:19], v[152:155], v[184:187], v[16:19]
	v_mfma_f32_16x16x32_bf16 v[12:15], v[156:159], v[180:183], v[12:15]
	v_mfma_f32_16x16x32_bf16 v[12:15], v[160:163], v[184:187], v[12:15]
	v_mfma_f32_16x16x32_bf16 v[8:11], v[148:151], v[188:191], v[8:11]
	v_mfma_f32_16x16x32_bf16 v[8:11], v[152:155], v[192:195], v[8:11]
	v_mfma_f32_16x16x32_bf16 v[2:5], v[156:159], v[188:191], v[4:7]
	v_mfma_f32_16x16x32_bf16 v[2:5], v[160:163], v[192:195], v[2:5]
	s_barrier
	s_add_i32 s66, 0, 0x18000
	v_add_u32_e32 v0, s66, v228
	s_add_i32 s67, 0, 0x1c000
	ds_read_b128 v[132:135], v0
	ds_read_b128 v[136:139], v0 offset:1024
	ds_read_b128 v[140:143], v0 offset:2048
	ds_read_b128 v[144:147], v0 offset:3072
	v_add_u32_e32 v0, s67, v228
	ds_read_b128 v[148:151], v0
	ds_read_b128 v[152:155], v0 offset:1024
	ds_read_b128 v[156:159], v0 offset:2048
	ds_read_b128 v[160:163], v0 offset:3072
	s_add_u32 s42, s42, 0x80000
	s_addc_u32 s43, s43, 0
	s_mov_b32 m0, s48
	v_lshl_add_u64 v[6:7], s[42:43], 0, v[206:207]
	ds_read_b128 v[164:167], v230 offset:32768
	ds_read_b128 v[168:171], v230 offset:33792
	ds_read_b128 v[172:175], v230 offset:34816
	ds_read_b128 v[176:179], v230 offset:35840
	ds_read_b128 v[180:183], v230 offset:36864
	ds_read_b128 v[184:187], v230 offset:37888
	ds_read_b128 v[188:191], v230 offset:38912
	ds_read_b128 v[192:195], v230 offset:39936
	global_load_lds_dwordx4 v[6:7], off
	v_lshl_add_u64 v[6:7], s[42:43], 0, v[202:203]
	s_mov_b32 m0, s49
	s_nop 0
	global_load_lds_dwordx4 v[6:7], off
	s_waitcnt vmcnt(8)
	s_waitcnt lgkmcnt(0)
	s_barrier
	v_mfma_f32_16x16x32_bf16 v[128:131], v[132:135], v[164:167], v[128:131]
	v_mfma_f32_16x16x32_bf16 v[128:131], v[136:139], v[168:171], v[128:131]
	v_mfma_f32_16x16x32_bf16 v[124:127], v[140:143], v[164:167], v[124:127]
	v_mfma_f32_16x16x32_bf16 v[124:127], v[144:147], v[168:171], v[124:127]
	v_mfma_f32_16x16x32_bf16 v[120:123], v[132:135], v[172:175], v[120:123]
	v_mfma_f32_16x16x32_bf16 v[120:123], v[136:139], v[176:179], v[120:123]
	v_mfma_f32_16x16x32_bf16 v[116:119], v[140:143], v[172:175], v[116:119]
	v_mfma_f32_16x16x32_bf16 v[116:119], v[144:147], v[176:179], v[116:119]
	v_mfma_f32_16x16x32_bf16 v[112:115], v[132:135], v[180:183], v[112:115]
	v_mfma_f32_16x16x32_bf16 v[112:115], v[136:139], v[184:187], v[112:115]
	v_mfma_f32_16x16x32_bf16 v[108:111], v[140:143], v[180:183], v[108:111]
	v_mfma_f32_16x16x32_bf16 v[108:111], v[144:147], v[184:187], v[108:111]
	v_mfma_f32_16x16x32_bf16 v[104:107], v[132:135], v[188:191], v[104:107]
	v_mfma_f32_16x16x32_bf16 v[104:107], v[136:139], v[192:195], v[104:107]
	v_mfma_f32_16x16x32_bf16 v[100:103], v[140:143], v[188:191], v[100:103]
	v_mfma_f32_16x16x32_bf16 v[100:103], v[144:147], v[192:195], v[100:103]
	v_mfma_f32_16x16x32_bf16 v[96:99], v[148:151], v[164:167], v[96:99]
	v_mfma_f32_16x16x32_bf16 v[96:99], v[152:155], v[168:171], v[96:99]
	v_mfma_f32_16x16x32_bf16 v[92:95], v[156:159], v[164:167], v[92:95]
	v_mfma_f32_16x16x32_bf16 v[92:95], v[160:163], v[168:171], v[92:95]
	v_mfma_f32_16x16x32_bf16 v[88:91], v[148:151], v[172:175], v[88:91]
	v_mfma_f32_16x16x32_bf16 v[88:91], v[152:155], v[176:179], v[88:91]
	v_mfma_f32_16x16x32_bf16 v[84:87], v[156:159], v[172:175], v[84:87]
	v_mfma_f32_16x16x32_bf16 v[84:87], v[160:163], v[176:179], v[84:87]
	v_mfma_f32_16x16x32_bf16 v[80:83], v[148:151], v[180:183], v[80:83]
	v_mfma_f32_16x16x32_bf16 v[80:83], v[152:155], v[184:187], v[80:83]
	v_mfma_f32_16x16x32_bf16 v[76:79], v[156:159], v[180:183], v[76:79]
	v_mfma_f32_16x16x32_bf16 v[76:79], v[160:163], v[184:187], v[76:79]
	v_mfma_f32_16x16x32_bf16 v[72:75], v[148:151], v[188:191], v[72:75]
	v_mfma_f32_16x16x32_bf16 v[72:75], v[152:155], v[192:195], v[72:75]
	v_mfma_f32_16x16x32_bf16 v[68:71], v[156:159], v[188:191], v[68:71]
	v_mfma_f32_16x16x32_bf16 v[68:71], v[160:163], v[192:195], v[68:71]
	s_barrier
	s_add_i32 s42, s66, s15
	v_lshl_add_u64 v[6:7], v[212:213], 0, s[12:13]
	s_mov_b32 m0, s42
	ds_read_b128 v[164:167], v230 offset:49152
	ds_read_b128 v[168:171], v230 offset:50176
	ds_read_b128 v[172:175], v230 offset:51200
	ds_read_b128 v[176:179], v230 offset:52224
	ds_read_b128 v[180:183], v230 offset:53248
	ds_read_b128 v[184:187], v230 offset:54272
	ds_read_b128 v[188:191], v230 offset:55296
	ds_read_b128 v[192:195], v230 offset:56320
	global_load_lds_dwordx4 v[6:7], off
	s_add_i32 m0, s42, 0x2000
	s_add_u32 s34, s34, 0x80080
	v_lshl_add_u64 v[6:7], v[214:215], 0, s[12:13]
	s_addc_u32 s35, s35, 0
	s_add_i32 s42, s67, s15
	global_load_lds_dwordx4 v[6:7], off
	v_lshl_add_u64 v[6:7], s[34:35], 0, v[204:205]
	s_mov_b32 m0, s42
	s_nop 0
	global_load_lds_dwordx4 v[6:7], off
	v_lshl_add_u64 v[6:7], s[34:35], 0, v[200:201]
	s_add_i32 m0, s42, 0x2000
	s_nop 0
	global_load_lds_dwordx4 v[6:7], off
	v_lshl_add_u64 v[6:7], v[216:217], 0, s[12:13]
	s_mov_b32 m0, s50
	s_nop 0
	global_load_lds_dwordx4 v[6:7], off
	v_lshl_add_u64 v[6:7], v[218:219], 0, s[12:13]
	s_mov_b32 m0, s51
	s_nop 0
	global_load_lds_dwordx4 v[6:7], off
	s_waitcnt vmcnt(8)
	s_waitcnt lgkmcnt(0)
	s_barrier
	v_mfma_f32_16x16x32_bf16 v[64:67], v[132:135], v[164:167], v[64:67]
	v_mfma_f32_16x16x32_bf16 v[64:67], v[136:139], v[168:171], v[64:67]
	v_mfma_f32_16x16x32_bf16 v[60:63], v[140:143], v[164:167], v[60:63]
	v_mfma_f32_16x16x32_bf16 v[60:63], v[144:147], v[168:171], v[60:63]
	v_mfma_f32_16x16x32_bf16 v[56:59], v[132:135], v[172:175], v[56:59]
	v_mfma_f32_16x16x32_bf16 v[56:59], v[136:139], v[176:179], v[56:59]
	v_mfma_f32_16x16x32_bf16 v[52:55], v[140:143], v[172:175], v[52:55]
	v_mfma_f32_16x16x32_bf16 v[52:55], v[144:147], v[176:179], v[52:55]
	v_mfma_f32_16x16x32_bf16 v[48:51], v[132:135], v[180:183], v[48:51]
	v_mfma_f32_16x16x32_bf16 v[48:51], v[136:139], v[184:187], v[48:51]
	v_mfma_f32_16x16x32_bf16 v[44:47], v[140:143], v[180:183], v[44:47]
	v_mfma_f32_16x16x32_bf16 v[44:47], v[144:147], v[184:187], v[44:47]
	v_mfma_f32_16x16x32_bf16 v[40:43], v[132:135], v[188:191], v[40:43]
	v_mfma_f32_16x16x32_bf16 v[40:43], v[136:139], v[192:195], v[40:43]
	v_mfma_f32_16x16x32_bf16 v[36:39], v[140:143], v[188:191], v[36:39]
	v_mfma_f32_16x16x32_bf16 v[36:39], v[144:147], v[192:195], v[36:39]
	v_mfma_f32_16x16x32_bf16 v[32:35], v[148:151], v[164:167], v[32:35]
	v_mfma_f32_16x16x32_bf16 v[32:35], v[152:155], v[168:171], v[32:35]
	v_mfma_f32_16x16x32_bf16 v[28:31], v[156:159], v[164:167], v[28:31]
	v_mfma_f32_16x16x32_bf16 v[28:31], v[160:163], v[168:171], v[28:31]
	v_mfma_f32_16x16x32_bf16 v[24:27], v[148:151], v[172:175], v[24:27]
	v_mfma_f32_16x16x32_bf16 v[24:27], v[152:155], v[176:179], v[24:27]
	v_mfma_f32_16x16x32_bf16 v[20:23], v[156:159], v[172:175], v[20:23]
	v_mfma_f32_16x16x32_bf16 v[20:23], v[160:163], v[176:179], v[20:23]
	v_mfma_f32_16x16x32_bf16 v[16:19], v[148:151], v[180:183], v[16:19]
	v_mfma_f32_16x16x32_bf16 v[16:19], v[152:155], v[184:187], v[16:19]
	v_mfma_f32_16x16x32_bf16 v[12:15], v[156:159], v[180:183], v[12:15]
	v_mfma_f32_16x16x32_bf16 v[12:15], v[160:163], v[184:187], v[12:15]
	v_mfma_f32_16x16x32_bf16 v[6:9], v[148:151], v[188:191], v[8:11]
	v_mfma_f32_16x16x32_bf16 v[8:11], v[152:155], v[192:195], v[6:9]
	v_mfma_f32_16x16x32_bf16 v[2:5], v[156:159], v[188:191], v[2:5]
	v_mfma_f32_16x16x32_bf16 v[4:7], v[160:163], v[192:195], v[2:5]
	s_barrier
	s_add_i32 s57, s57, 2
	s_add_u32 s30, s30, 0x100
	s_addc_u32 s31, s31, 0
	s_add_u32 s55, s55, 0x100
	s_addc_u32 s56, s56, 0
	s_cmp_gt_u32 s57, 29
	s_cbranch_scc0 .LBB0_577
	s_and_b64 vcc, exec, s[20:21]
	s_cbranch_vccz .LBB0_580
	s_barrier

.LBB0_779:
	s_add_u32 s34, s30, 0xfff80080
	s_addc_u32 s35, s31, -1
	s_add_i32 s66, 0, 0x10000
	s_cmp_eq_u32 s57, 28
	s_cselect_b32 s43, s25, s35
	s_cselect_b32 s42, s53, s34
	s_cselect_b32 s35, s23, s56
	s_cselect_b32 s34, s54, s55
	s_add_i32 s73, 0, 0x14000
	v_add_u32_e32 v114, s66, v157
	v_add_u32_e32 v156, s73, v157
	ds_read_b128 v[90:93], v114
	ds_read_b128 v[94:97], v114 offset:1024
	ds_read_b128 v[106:109], v114 offset:2048
	ds_read_b128 v[114:117], v114 offset:3072
	ds_read_b128 v[162:165], v156
	ds_read_b128 v[166:169], v156 offset:1024
	ds_read_b128 v[170:173], v156 offset:2048
	ds_read_b128 v[174:177], v156 offset:3072
	v_lshl_add_u64 v[158:159], s[30:31], 0, v[152:153]
	s_add_i32 m0, s14, 0xc000
	ds_read_b128 v[178:181], v161
	ds_read_b128 v[182:185], v161 offset:1024
	ds_read_b128 v[186:189], v161 offset:2048
	ds_read_b128 v[190:193], v161 offset:3072
	ds_read_b128 v[200:203], v161 offset:4096
	ds_read_b128 v[204:207], v161 offset:5120
	ds_read_b128 v[208:211], v161 offset:6144
	ds_read_b128 v[212:215], v161 offset:7168
	global_load_lds_dwordx4 v[158:159], off
	v_lshl_add_u64 v[158:159], s[30:31], 0, v[154:155]
	s_add_i32 m0, s14, 0xe000
	s_nop 0
	global_load_lds_dwordx4 v[158:159], off
	s_waitcnt vmcnt(8)
	s_waitcnt lgkmcnt(0)
	s_barrier
	v_mfma_i32_16x16x64_i8 v[142:145], v[90:93], v[178:181], v[142:145]
	v_mfma_i32_16x16x64_i8 v[142:145], v[94:97], v[182:185], v[142:145]
	v_mfma_i32_16x16x64_i8 v[138:141], v[106:109], v[178:181], v[138:141]
	v_mfma_i32_16x16x64_i8 v[138:141], v[114:117], v[182:185], v[138:141]
	v_mfma_i32_16x16x64_i8 v[126:129], v[90:93], v[186:189], v[126:129]
	v_mfma_i32_16x16x64_i8 v[126:129], v[94:97], v[190:193], v[126:129]
	v_mfma_i32_16x16x64_i8 v[122:125], v[106:109], v[186:189], v[122:125]
	v_mfma_i32_16x16x64_i8 v[122:125], v[114:117], v[190:193], v[122:125]
	v_mfma_i32_16x16x64_i8 v[102:105], v[90:93], v[200:203], v[102:105]
	v_mfma_i32_16x16x64_i8 v[102:105], v[94:97], v[204:207], v[102:105]
	v_mfma_i32_16x16x64_i8 v[98:101], v[106:109], v[200:203], v[98:101]
	v_mfma_i32_16x16x64_i8 v[98:101], v[114:117], v[204:207], v[98:101]
	v_mfma_i32_16x16x64_i8 v[78:81], v[90:93], v[208:211], v[78:81]
	v_mfma_i32_16x16x64_i8 v[78:81], v[94:97], v[212:215], v[78:81]
	v_mfma_i32_16x16x64_i8 v[74:77], v[106:109], v[208:211], v[74:77]
	v_mfma_i32_16x16x64_i8 v[74:77], v[114:117], v[212:215], v[74:77]
	v_mfma_i32_16x16x64_i8 v[134:137], v[162:165], v[178:181], v[134:137]
	v_mfma_i32_16x16x64_i8 v[134:137], v[166:169], v[182:185], v[134:137]
	v_mfma_i32_16x16x64_i8 v[130:133], v[170:173], v[178:181], v[130:133]
	v_mfma_i32_16x16x64_i8 v[130:133], v[174:177], v[182:185], v[130:133]
	v_mfma_i32_16x16x64_i8 v[118:121], v[162:165], v[186:189], v[118:121]
	v_mfma_i32_16x16x64_i8 v[118:121], v[166:169], v[190:193], v[118:121]
	v_mfma_i32_16x16x64_i8 v[110:113], v[170:173], v[186:189], v[110:113]
	v_mfma_i32_16x16x64_i8 v[110:113], v[174:177], v[190:193], v[110:113]
	v_mfma_i32_16x16x64_i8 v[86:89], v[162:165], v[200:203], v[86:89]
	v_mfma_i32_16x16x64_i8 v[86:89], v[166:169], v[204:207], v[86:89]
	v_mfma_i32_16x16x64_i8 v[82:85], v[170:173], v[200:203], v[82:85]
	v_mfma_i32_16x16x64_i8 v[82:85], v[174:177], v[204:207], v[82:85]
	v_mfma_i32_16x16x64_i8 v[70:73], v[162:165], v[208:211], v[70:73]
	v_mfma_i32_16x16x64_i8 v[70:73], v[166:169], v[212:215], v[70:73]
	v_mfma_i32_16x16x64_i8 v[66:69], v[170:173], v[208:211], v[66:69]
	v_mfma_i32_16x16x64_i8 v[66:69], v[174:177], v[212:215], v[66:69]
	s_barrier
	s_add_i32 s66, s66, s9
	v_lshl_add_u64 v[158:159], s[34:35], 0, v[0:1]
	s_mov_b32 m0, s66
	ds_read_b128 v[178:181], v161 offset:16384
	ds_read_b128 v[182:185], v161 offset:17408
	ds_read_b128 v[186:189], v161 offset:18432
	ds_read_b128 v[190:193], v161 offset:19456
	ds_read_b128 v[200:203], v161 offset:20480
	ds_read_b128 v[204:207], v161 offset:21504
	ds_read_b128 v[208:211], v161 offset:22528
	ds_read_b128 v[212:215], v161 offset:23552
	global_load_lds_dwordx4 v[158:159], off
	s_add_i32 m0, s66, 0x2000
	s_add_u32 s66, s34, 0x80000
	v_lshl_add_u64 v[194:195], s[34:35], 0, v[146:147]
	s_addc_u32 s67, s35, 0
	s_add_i32 s73, s73, s9
	global_load_lds_dwordx4 v[194:195], off
	v_lshl_add_u64 v[216:217], s[66:67], 0, v[0:1]
	s_mov_b32 m0, s73
	v_lshl_add_u64 v[218:219], s[42:43], 0, v[148:149]
	global_load_lds_dwordx4 v[216:217], off
	v_lshl_add_u64 v[216:217], s[66:67], 0, v[146:147]
	s_add_i32 m0, s73, 0x2000
	s_nop 0
	global_load_lds_dwordx4 v[216:217], off
	v_lshl_add_u64 v[216:217], s[42:43], 0, v[150:151]
	s_mov_b32 m0, s14
	s_nop 0
	global_load_lds_dwordx4 v[216:217], off
	s_mov_b32 m0, s15
	s_nop 0
	global_load_lds_dwordx4 v[218:219], off
	s_waitcnt vmcnt(8)
	s_waitcnt lgkmcnt(0)
	s_barrier
	v_mfma_i32_16x16x64_i8 v[62:65], v[90:93], v[178:181], v[62:65]
	v_mfma_i32_16x16x64_i8 v[62:65], v[94:97], v[182:185], v[62:65]
	v_mfma_i32_16x16x64_i8 v[58:61], v[106:109], v[178:181], v[58:61]
	v_mfma_i32_16x16x64_i8 v[58:61], v[114:117], v[182:185], v[58:61]
	v_mfma_i32_16x16x64_i8 v[46:49], v[90:93], v[186:189], v[46:49]
	v_mfma_i32_16x16x64_i8 v[46:49], v[94:97], v[190:193], v[46:49]
	v_mfma_i32_16x16x64_i8 v[42:45], v[106:109], v[186:189], v[42:45]
	v_mfma_i32_16x16x64_i8 v[42:45], v[114:117], v[190:193], v[42:45]
	v_mfma_i32_16x16x64_i8 v[30:33], v[90:93], v[200:203], v[30:33]
	v_mfma_i32_16x16x64_i8 v[30:33], v[94:97], v[204:207], v[30:33]
	v_mfma_i32_16x16x64_i8 v[26:29], v[106:109], v[200:203], v[26:29]
	v_mfma_i32_16x16x64_i8 v[26:29], v[114:117], v[204:207], v[26:29]
	v_mfma_i32_16x16x64_i8 v[14:17], v[90:93], v[208:211], v[14:17]
	v_mfma_i32_16x16x64_i8 v[14:17], v[94:97], v[212:215], v[14:17]
	v_mfma_i32_16x16x64_i8 v[10:13], v[106:109], v[208:211], v[10:13]
	v_mfma_i32_16x16x64_i8 v[10:13], v[114:117], v[212:215], v[10:13]
	v_mfma_i32_16x16x64_i8 v[54:57], v[162:165], v[178:181], v[54:57]
	v_mfma_i32_16x16x64_i8 v[54:57], v[166:169], v[182:185], v[54:57]
	v_mfma_i32_16x16x64_i8 v[50:53], v[170:173], v[178:181], v[50:53]
	v_mfma_i32_16x16x64_i8 v[50:53], v[174:177], v[182:185], v[50:53]
	v_mfma_i32_16x16x64_i8 v[38:41], v[162:165], v[186:189], v[38:41]
	v_mfma_i32_16x16x64_i8 v[38:41], v[166:169], v[190:193], v[38:41]
	v_mfma_i32_16x16x64_i8 v[34:37], v[170:173], v[186:189], v[34:37]
	v_mfma_i32_16x16x64_i8 v[34:37], v[174:177], v[190:193], v[34:37]
	v_mfma_i32_16x16x64_i8 v[22:25], v[162:165], v[200:203], v[22:25]
	v_mfma_i32_16x16x64_i8 v[22:25], v[166:169], v[204:207], v[22:25]
	v_mfma_i32_16x16x64_i8 v[18:21], v[170:173], v[200:203], v[18:21]
	v_mfma_i32_16x16x64_i8 v[18:21], v[174:177], v[204:207], v[18:21]
	v_mfma_i32_16x16x64_i8 v[6:9], v[162:165], v[208:211], v[6:9]
	v_mfma_i32_16x16x64_i8 v[6:9], v[166:169], v[212:215], v[6:9]
	v_mfma_i32_16x16x64_i8 v[2:5], v[170:173], v[208:211], v[2:5]
	v_mfma_i32_16x16x64_i8 v[2:5], v[174:177], v[212:215], v[2:5]
	s_barrier
	s_add_i32 s66, 0, 0x18000
	s_add_i32 s67, 0, 0x1c000
	v_add_u32_e32 v114, s66, v157
	v_add_u32_e32 v156, s67, v157
	ds_read_b128 v[90:93], v114
	ds_read_b128 v[94:97], v114 offset:1024
	ds_read_b128 v[106:109], v114 offset:2048
	ds_read_b128 v[114:117], v114 offset:3072
	ds_read_b128 v[162:165], v156
	ds_read_b128 v[166:169], v156 offset:1024
	ds_read_b128 v[170:173], v156 offset:2048
	ds_read_b128 v[174:177], v156 offset:3072
	s_add_u32 s42, s42, 0x80000
	s_addc_u32 s43, s43, 0
	s_mov_b32 m0, s46
	v_lshl_add_u64 v[220:221], s[42:43], 0, v[150:151]
	ds_read_b128 v[178:181], v161 offset:32768
	ds_read_b128 v[182:185], v161 offset:33792
	ds_read_b128 v[186:189], v161 offset:34816
	ds_read_b128 v[190:193], v161 offset:35840
	ds_read_b128 v[200:203], v161 offset:36864
	ds_read_b128 v[204:207], v161 offset:37888
	ds_read_b128 v[208:211], v161 offset:38912
	ds_read_b128 v[212:215], v161 offset:39936
	global_load_lds_dwordx4 v[220:221], off
	v_lshl_add_u64 v[220:221], s[42:43], 0, v[148:149]
	s_mov_b32 m0, s47
	s_nop 0
	global_load_lds_dwordx4 v[220:221], off
	s_waitcnt vmcnt(8)
	s_waitcnt lgkmcnt(0)
	s_barrier
	v_mfma_i32_16x16x64_i8 v[142:145], v[90:93], v[178:181], v[142:145]
	v_mfma_i32_16x16x64_i8 v[142:145], v[94:97], v[182:185], v[142:145]
	v_mfma_i32_16x16x64_i8 v[138:141], v[106:109], v[178:181], v[138:141]
	v_mfma_i32_16x16x64_i8 v[138:141], v[114:117], v[182:185], v[138:141]
	v_mfma_i32_16x16x64_i8 v[126:129], v[90:93], v[186:189], v[126:129]
	v_mfma_i32_16x16x64_i8 v[126:129], v[94:97], v[190:193], v[126:129]
	v_mfma_i32_16x16x64_i8 v[122:125], v[106:109], v[186:189], v[122:125]
	v_mfma_i32_16x16x64_i8 v[122:125], v[114:117], v[190:193], v[122:125]
	v_mfma_i32_16x16x64_i8 v[102:105], v[90:93], v[200:203], v[102:105]
	v_mfma_i32_16x16x64_i8 v[102:105], v[94:97], v[204:207], v[102:105]
	v_mfma_i32_16x16x64_i8 v[98:101], v[106:109], v[200:203], v[98:101]
	v_mfma_i32_16x16x64_i8 v[98:101], v[114:117], v[204:207], v[98:101]
	v_mfma_i32_16x16x64_i8 v[78:81], v[90:93], v[208:211], v[78:81]
	v_mfma_i32_16x16x64_i8 v[78:81], v[94:97], v[212:215], v[78:81]
	v_mfma_i32_16x16x64_i8 v[74:77], v[106:109], v[208:211], v[74:77]
	v_mfma_i32_16x16x64_i8 v[74:77], v[114:117], v[212:215], v[74:77]
	v_mfma_i32_16x16x64_i8 v[134:137], v[162:165], v[178:181], v[134:137]
	v_mfma_i32_16x16x64_i8 v[134:137], v[166:169], v[182:185], v[134:137]
	v_mfma_i32_16x16x64_i8 v[130:133], v[170:173], v[178:181], v[130:133]
	v_mfma_i32_16x16x64_i8 v[130:133], v[174:177], v[182:185], v[130:133]
	v_mfma_i32_16x16x64_i8 v[118:121], v[162:165], v[186:189], v[118:121]
	v_mfma_i32_16x16x64_i8 v[118:121], v[166:169], v[190:193], v[118:121]
	v_mfma_i32_16x16x64_i8 v[110:113], v[170:173], v[186:189], v[110:113]
	v_mfma_i32_16x16x64_i8 v[110:113], v[174:177], v[190:193], v[110:113]
	v_mfma_i32_16x16x64_i8 v[86:89], v[162:165], v[200:203], v[86:89]
	v_mfma_i32_16x16x64_i8 v[86:89], v[166:169], v[204:207], v[86:89]
	v_mfma_i32_16x16x64_i8 v[82:85], v[170:173], v[200:203], v[82:85]
	v_mfma_i32_16x16x64_i8 v[82:85], v[174:177], v[204:207], v[82:85]
	v_mfma_i32_16x16x64_i8 v[70:73], v[162:165], v[208:211], v[70:73]
	v_mfma_i32_16x16x64_i8 v[70:73], v[166:169], v[212:215], v[70:73]
	v_mfma_i32_16x16x64_i8 v[66:69], v[170:173], v[208:211], v[66:69]
	v_mfma_i32_16x16x64_i8 v[66:69], v[174:177], v[212:215], v[66:69]
	s_barrier
	s_add_i32 s42, s66, s9
	v_lshl_add_u64 v[158:159], v[158:159], 0, s[12:13]
	s_mov_b32 m0, s42
	ds_read_b128 v[178:181], v161 offset:49152
	ds_read_b128 v[182:185], v161 offset:50176
	ds_read_b128 v[186:189], v161 offset:51200
	ds_read_b128 v[190:193], v161 offset:52224
	ds_read_b128 v[200:203], v161 offset:53248
	ds_read_b128 v[204:207], v161 offset:54272
	ds_read_b128 v[208:211], v161 offset:55296
	ds_read_b128 v[212:215], v161 offset:56320
	global_load_lds_dwordx4 v[158:159], off
	s_add_i32 m0, s42, 0x2000
	s_add_u32 s34, s34, 0x80080
	v_lshl_add_u64 v[158:159], v[194:195], 0, s[12:13]
	s_addc_u32 s35, s35, 0
	s_add_i32 s42, s67, s9
	global_load_lds_dwordx4 v[158:159], off
	v_lshl_add_u64 v[158:159], s[34:35], 0, v[0:1]
	s_mov_b32 m0, s42
	s_nop 0
	global_load_lds_dwordx4 v[158:159], off
	v_lshl_add_u64 v[158:159], s[34:35], 0, v[146:147]
	s_add_i32 m0, s42, 0x2000
	s_nop 0
	global_load_lds_dwordx4 v[158:159], off
	v_lshl_add_u64 v[158:159], v[216:217], 0, s[12:13]
	s_mov_b32 m0, s50
	s_nop 0
	global_load_lds_dwordx4 v[158:159], off
	v_lshl_add_u64 v[158:159], v[218:219], 0, s[12:13]
	s_mov_b32 m0, s51
	s_nop 0
	global_load_lds_dwordx4 v[158:159], off
	s_waitcnt vmcnt(8)
	s_waitcnt lgkmcnt(0)
	s_barrier
	v_mfma_i32_16x16x64_i8 v[62:65], v[90:93], v[178:181], v[62:65]
	v_mfma_i32_16x16x64_i8 v[62:65], v[94:97], v[182:185], v[62:65]
	v_mfma_i32_16x16x64_i8 v[58:61], v[106:109], v[178:181], v[58:61]
	v_mfma_i32_16x16x64_i8 v[58:61], v[114:117], v[182:185], v[58:61]
	v_mfma_i32_16x16x64_i8 v[46:49], v[90:93], v[186:189], v[46:49]
	v_mfma_i32_16x16x64_i8 v[46:49], v[94:97], v[190:193], v[46:49]
	v_mfma_i32_16x16x64_i8 v[42:45], v[106:109], v[186:189], v[42:45]
	v_mfma_i32_16x16x64_i8 v[42:45], v[114:117], v[190:193], v[42:45]
	v_mfma_i32_16x16x64_i8 v[30:33], v[90:93], v[200:203], v[30:33]
	v_mfma_i32_16x16x64_i8 v[30:33], v[94:97], v[204:207], v[30:33]
	v_mfma_i32_16x16x64_i8 v[26:29], v[106:109], v[200:203], v[26:29]
	v_mfma_i32_16x16x64_i8 v[26:29], v[114:117], v[204:207], v[26:29]
	v_mfma_i32_16x16x64_i8 v[14:17], v[90:93], v[208:211], v[14:17]
	v_mfma_i32_16x16x64_i8 v[14:17], v[94:97], v[212:215], v[14:17]
	v_mfma_i32_16x16x64_i8 v[10:13], v[106:109], v[208:211], v[10:13]
	v_mfma_i32_16x16x64_i8 v[10:13], v[114:117], v[212:215], v[10:13]
	v_mfma_i32_16x16x64_i8 v[54:57], v[162:165], v[178:181], v[54:57]
	v_mfma_i32_16x16x64_i8 v[54:57], v[166:169], v[182:185], v[54:57]
	v_mfma_i32_16x16x64_i8 v[50:53], v[170:173], v[178:181], v[50:53]
	v_mfma_i32_16x16x64_i8 v[50:53], v[174:177], v[182:185], v[50:53]
	v_mfma_i32_16x16x64_i8 v[38:41], v[162:165], v[186:189], v[38:41]
	v_mfma_i32_16x16x64_i8 v[38:41], v[166:169], v[190:193], v[38:41]
	v_mfma_i32_16x16x64_i8 v[34:37], v[170:173], v[186:189], v[34:37]
	v_mfma_i32_16x16x64_i8 v[34:37], v[174:177], v[190:193], v[34:37]
	v_mfma_i32_16x16x64_i8 v[22:25], v[162:165], v[200:203], v[22:25]
	v_mfma_i32_16x16x64_i8 v[22:25], v[166:169], v[204:207], v[22:25]
	v_mfma_i32_16x16x64_i8 v[18:21], v[170:173], v[200:203], v[18:21]
	v_mfma_i32_16x16x64_i8 v[18:21], v[174:177], v[204:207], v[18:21]
	v_mfma_i32_16x16x64_i8 v[6:9], v[162:165], v[208:211], v[6:9]
	v_mfma_i32_16x16x64_i8 v[6:9], v[166:169], v[212:215], v[6:9]
	v_mfma_i32_16x16x64_i8 v[2:5], v[170:173], v[208:211], v[2:5]
	v_mfma_i32_16x16x64_i8 v[2:5], v[174:177], v[212:215], v[2:5]
	s_barrier
	s_add_i32 s57, s57, 2
	s_add_u32 s30, s30, 0x100
	s_addc_u32 s31, s31, 0
	s_add_u32 s55, s55, 0x100
	s_addc_u32 s56, s56, 0
	s_cmp_gt_u32 s57, 29
	s_cbranch_scc0 .LBB0_779
	s_and_b64 vcc, exec, s[20:21]
	s_mov_b32 s54, 0x5c401000
	s_cbranch_vccz .LBB0_782
	s_barrier

.LBB0_801:
	s_add_u32 s34, s30, 0xfff00080
	s_addc_u32 s35, s31, -1
	s_add_i32 s54, 0, 0x10000
	s_cmp_eq_u32 s53, 60
	s_cselect_b32 s41, s25, s35
	s_cselect_b32 s40, s49, s34
	s_cselect_b32 s35, s23, s52
	s_cselect_b32 s34, s50, s51
	s_add_i32 s56, 0, 0x14000
	v_add_u32_e32 v156, s54, v141
	v_add_u32_e32 v172, s56, v141
	ds_read_b128 v[144:147], v156
	ds_read_b128 v[148:151], v156 offset:1024
	ds_read_b128 v[152:155], v156 offset:2048
	ds_read_b128 v[156:159], v156 offset:3072
	ds_read_b128 v[160:163], v172
	ds_read_b128 v[164:167], v172 offset:1024
	ds_read_b128 v[168:171], v172 offset:2048
	ds_read_b128 v[172:175], v172 offset:3072
	v_lshl_add_u64 v[212:213], s[30:31], 0, v[136:137]
	s_add_i32 m0, s14, 0xc000
	ds_read_b128 v[176:179], v143
	ds_read_b128 v[180:183], v143 offset:1024
	ds_read_b128 v[184:187], v143 offset:2048
	ds_read_b128 v[188:191], v143 offset:3072
	ds_read_b128 v[192:195], v143 offset:4096
	ds_read_b128 v[200:203], v143 offset:5120
	ds_read_b128 v[204:207], v143 offset:6144
	ds_read_b128 v[208:211], v143 offset:7168
	global_load_lds_dwordx4 v[212:213], off
	v_lshl_add_u64 v[212:213], s[30:31], 0, v[138:139]
	s_add_i32 m0, s14, 0xe000
	s_nop 0
	global_load_lds_dwordx4 v[212:213], off
	s_waitcnt vmcnt(8)
	s_waitcnt lgkmcnt(0)
	s_barrier
	v_mfma_f32_16x16x32_bf16 v[126:129], v[144:147], v[176:179], v[126:129]
	v_mfma_f32_16x16x32_bf16 v[126:129], v[148:151], v[180:183], v[126:129]
	v_mfma_f32_16x16x32_bf16 v[122:125], v[152:155], v[176:179], v[122:125]
	v_mfma_f32_16x16x32_bf16 v[122:125], v[156:159], v[180:183], v[122:125]
	v_mfma_f32_16x16x32_bf16 v[118:121], v[144:147], v[184:187], v[118:121]
	v_mfma_f32_16x16x32_bf16 v[118:121], v[148:151], v[188:191], v[118:121]
	v_mfma_f32_16x16x32_bf16 v[114:117], v[152:155], v[184:187], v[114:117]
	v_mfma_f32_16x16x32_bf16 v[114:117], v[156:159], v[188:191], v[114:117]
	v_mfma_f32_16x16x32_bf16 v[102:105], v[144:147], v[192:195], v[102:105]
	v_mfma_f32_16x16x32_bf16 v[102:105], v[148:151], v[200:203], v[102:105]
	v_mfma_f32_16x16x32_bf16 v[98:101], v[152:155], v[192:195], v[98:101]
	v_mfma_f32_16x16x32_bf16 v[98:101], v[156:159], v[200:203], v[98:101]
	v_mfma_f32_16x16x32_bf16 v[86:89], v[144:147], v[204:207], v[86:89]
	v_mfma_f32_16x16x32_bf16 v[86:89], v[148:151], v[208:211], v[86:89]
	v_mfma_f32_16x16x32_bf16 v[82:85], v[152:155], v[204:207], v[82:85]
	v_mfma_f32_16x16x32_bf16 v[82:85], v[156:159], v[208:211], v[82:85]
	v_mfma_f32_16x16x32_bf16 v[110:113], v[160:163], v[176:179], v[110:113]
	v_mfma_f32_16x16x32_bf16 v[110:113], v[164:167], v[180:183], v[110:113]
	v_mfma_f32_16x16x32_bf16 v[106:109], v[168:171], v[176:179], v[106:109]
	v_mfma_f32_16x16x32_bf16 v[106:109], v[172:175], v[180:183], v[106:109]
	v_mfma_f32_16x16x32_bf16 v[94:97], v[160:163], v[184:187], v[94:97]
	v_mfma_f32_16x16x32_bf16 v[94:97], v[164:167], v[188:191], v[94:97]
	v_mfma_f32_16x16x32_bf16 v[90:93], v[168:171], v[184:187], v[90:93]
	v_mfma_f32_16x16x32_bf16 v[90:93], v[172:175], v[188:191], v[90:93]
	v_mfma_f32_16x16x32_bf16 v[78:81], v[160:163], v[192:195], v[78:81]
	v_mfma_f32_16x16x32_bf16 v[78:81], v[164:167], v[200:203], v[78:81]
	v_mfma_f32_16x16x32_bf16 v[74:77], v[168:171], v[192:195], v[74:77]
	v_mfma_f32_16x16x32_bf16 v[74:77], v[172:175], v[200:203], v[74:77]
	v_mfma_f32_16x16x32_bf16 v[70:73], v[160:163], v[204:207], v[70:73]
	v_mfma_f32_16x16x32_bf16 v[70:73], v[164:167], v[208:211], v[70:73]
	v_mfma_f32_16x16x32_bf16 v[66:69], v[168:171], v[204:207], v[66:69]
	v_mfma_f32_16x16x32_bf16 v[66:69], v[172:175], v[208:211], v[66:69]
	s_barrier
	s_add_i32 s54, s54, s9
	v_lshl_add_u64 v[212:213], s[34:35], 0, v[0:1]
	s_mov_b32 m0, s54
	ds_read_b128 v[176:179], v143 offset:16384
	ds_read_b128 v[180:183], v143 offset:17408
	ds_read_b128 v[184:187], v143 offset:18432
	ds_read_b128 v[188:191], v143 offset:19456
	ds_read_b128 v[192:195], v143 offset:20480
	ds_read_b128 v[200:203], v143 offset:21504
	ds_read_b128 v[204:207], v143 offset:22528
	ds_read_b128 v[208:211], v143 offset:23552
	global_load_lds_dwordx4 v[212:213], off
	s_add_i32 m0, s54, 0x2000
	s_add_u32 s54, s34, 0x100000
	v_lshl_add_u64 v[214:215], s[34:35], 0, v[130:131]
	s_addc_u32 s55, s35, 0
	s_add_i32 s56, s56, s9
	global_load_lds_dwordx4 v[214:215], off
	v_lshl_add_u64 v[216:217], s[54:55], 0, v[0:1]
	s_mov_b32 m0, s56
	v_lshl_add_u64 v[218:219], s[40:41], 0, v[132:133]
	global_load_lds_dwordx4 v[216:217], off
	v_lshl_add_u64 v[216:217], s[54:55], 0, v[130:131]
	s_add_i32 m0, s56, 0x2000
	s_nop 0
	global_load_lds_dwordx4 v[216:217], off
	v_lshl_add_u64 v[216:217], s[40:41], 0, v[134:135]
	s_mov_b32 m0, s14
	s_nop 0
	global_load_lds_dwordx4 v[216:217], off
	s_mov_b32 m0, s15
	s_nop 0
	global_load_lds_dwordx4 v[218:219], off
	s_waitcnt vmcnt(8)
	s_waitcnt lgkmcnt(0)
	s_barrier
	v_mfma_f32_16x16x32_bf16 v[62:65], v[144:147], v[176:179], v[62:65]
	v_mfma_f32_16x16x32_bf16 v[62:65], v[148:151], v[180:183], v[62:65]
	v_mfma_f32_16x16x32_bf16 v[58:61], v[152:155], v[176:179], v[58:61]
	v_mfma_f32_16x16x32_bf16 v[58:61], v[156:159], v[180:183], v[58:61]
	v_mfma_f32_16x16x32_bf16 v[54:57], v[144:147], v[184:187], v[54:57]
	v_mfma_f32_16x16x32_bf16 v[54:57], v[148:151], v[188:191], v[54:57]
	v_mfma_f32_16x16x32_bf16 v[50:53], v[152:155], v[184:187], v[50:53]
	v_mfma_f32_16x16x32_bf16 v[50:53], v[156:159], v[188:191], v[50:53]
	v_mfma_f32_16x16x32_bf16 v[38:41], v[144:147], v[192:195], v[38:41]
	v_mfma_f32_16x16x32_bf16 v[38:41], v[148:151], v[200:203], v[38:41]
	v_mfma_f32_16x16x32_bf16 v[34:37], v[152:155], v[192:195], v[34:37]
	v_mfma_f32_16x16x32_bf16 v[34:37], v[156:159], v[200:203], v[34:37]
	v_mfma_f32_16x16x32_bf16 v[22:25], v[144:147], v[204:207], v[22:25]
	v_mfma_f32_16x16x32_bf16 v[22:25], v[148:151], v[208:211], v[22:25]
	v_mfma_f32_16x16x32_bf16 v[18:21], v[152:155], v[204:207], v[18:21]
	v_mfma_f32_16x16x32_bf16 v[18:21], v[156:159], v[208:211], v[18:21]
	v_mfma_f32_16x16x32_bf16 v[46:49], v[160:163], v[176:179], v[46:49]
	v_mfma_f32_16x16x32_bf16 v[46:49], v[164:167], v[180:183], v[46:49]
	v_mfma_f32_16x16x32_bf16 v[42:45], v[168:171], v[176:179], v[42:45]
	v_mfma_f32_16x16x32_bf16 v[42:45], v[172:175], v[180:183], v[42:45]
	v_mfma_f32_16x16x32_bf16 v[30:33], v[160:163], v[184:187], v[30:33]
	v_mfma_f32_16x16x32_bf16 v[30:33], v[164:167], v[188:191], v[30:33]
	v_mfma_f32_16x16x32_bf16 v[26:29], v[168:171], v[184:187], v[26:29]
	v_mfma_f32_16x16x32_bf16 v[26:29], v[172:175], v[188:191], v[26:29]
	v_mfma_f32_16x16x32_bf16 v[14:17], v[160:163], v[192:195], v[14:17]
	v_mfma_f32_16x16x32_bf16 v[14:17], v[164:167], v[200:203], v[14:17]
	v_mfma_f32_16x16x32_bf16 v[10:13], v[168:171], v[192:195], v[10:13]
	v_mfma_f32_16x16x32_bf16 v[10:13], v[172:175], v[200:203], v[10:13]
	v_mfma_f32_16x16x32_bf16 v[6:9], v[160:163], v[204:207], v[6:9]
	v_mfma_f32_16x16x32_bf16 v[6:9], v[164:167], v[208:211], v[6:9]
	v_mfma_f32_16x16x32_bf16 v[2:5], v[168:171], v[204:207], v[2:5]
	v_mfma_f32_16x16x32_bf16 v[2:5], v[172:175], v[208:211], v[2:5]
	s_barrier
	s_add_i32 s54, 0, 0x18000
	s_add_i32 s55, 0, 0x1c000
	v_add_u32_e32 v156, s54, v141
	v_add_u32_e32 v172, s55, v141
	ds_read_b128 v[144:147], v156
	ds_read_b128 v[148:151], v156 offset:1024
	ds_read_b128 v[152:155], v156 offset:2048
	ds_read_b128 v[156:159], v156 offset:3072
	ds_read_b128 v[160:163], v172
	ds_read_b128 v[164:167], v172 offset:1024
	ds_read_b128 v[168:171], v172 offset:2048
	ds_read_b128 v[172:175], v172 offset:3072
	s_add_u32 s40, s40, 0x100000
	s_addc_u32 s41, s41, 0
	s_mov_b32 m0, s18
	v_lshl_add_u64 v[220:221], s[40:41], 0, v[134:135]
	ds_read_b128 v[176:179], v143 offset:32768
	ds_read_b128 v[180:183], v143 offset:33792
	ds_read_b128 v[184:187], v143 offset:34816
	ds_read_b128 v[188:191], v143 offset:35840
	ds_read_b128 v[192:195], v143 offset:36864
	ds_read_b128 v[200:203], v143 offset:37888
	ds_read_b128 v[204:207], v143 offset:38912
	ds_read_b128 v[208:211], v143 offset:39936
	global_load_lds_dwordx4 v[220:221], off
	v_lshl_add_u64 v[220:221], s[40:41], 0, v[132:133]
	s_mov_b32 m0, s19
	s_nop 0
	global_load_lds_dwordx4 v[220:221], off
	s_waitcnt vmcnt(8)
	s_waitcnt lgkmcnt(0)
	s_barrier
	v_mfma_f32_16x16x32_bf16 v[126:129], v[144:147], v[176:179], v[126:129]
	v_mfma_f32_16x16x32_bf16 v[126:129], v[148:151], v[180:183], v[126:129]
	v_mfma_f32_16x16x32_bf16 v[122:125], v[152:155], v[176:179], v[122:125]
	v_mfma_f32_16x16x32_bf16 v[122:125], v[156:159], v[180:183], v[122:125]
	v_mfma_f32_16x16x32_bf16 v[118:121], v[144:147], v[184:187], v[118:121]
	v_mfma_f32_16x16x32_bf16 v[118:121], v[148:151], v[188:191], v[118:121]
	v_mfma_f32_16x16x32_bf16 v[114:117], v[152:155], v[184:187], v[114:117]
	v_mfma_f32_16x16x32_bf16 v[114:117], v[156:159], v[188:191], v[114:117]
	v_mfma_f32_16x16x32_bf16 v[102:105], v[144:147], v[192:195], v[102:105]
	v_mfma_f32_16x16x32_bf16 v[102:105], v[148:151], v[200:203], v[102:105]
	v_mfma_f32_16x16x32_bf16 v[98:101], v[152:155], v[192:195], v[98:101]
	v_mfma_f32_16x16x32_bf16 v[98:101], v[156:159], v[200:203], v[98:101]
	v_mfma_f32_16x16x32_bf16 v[86:89], v[144:147], v[204:207], v[86:89]
	v_mfma_f32_16x16x32_bf16 v[86:89], v[148:151], v[208:211], v[86:89]
	v_mfma_f32_16x16x32_bf16 v[82:85], v[152:155], v[204:207], v[82:85]
	v_mfma_f32_16x16x32_bf16 v[82:85], v[156:159], v[208:211], v[82:85]
	v_mfma_f32_16x16x32_bf16 v[110:113], v[160:163], v[176:179], v[110:113]
	v_mfma_f32_16x16x32_bf16 v[110:113], v[164:167], v[180:183], v[110:113]
	v_mfma_f32_16x16x32_bf16 v[106:109], v[168:171], v[176:179], v[106:109]
	v_mfma_f32_16x16x32_bf16 v[106:109], v[172:175], v[180:183], v[106:109]
	v_mfma_f32_16x16x32_bf16 v[94:97], v[160:163], v[184:187], v[94:97]
	v_mfma_f32_16x16x32_bf16 v[94:97], v[164:167], v[188:191], v[94:97]
	v_mfma_f32_16x16x32_bf16 v[90:93], v[168:171], v[184:187], v[90:93]
	v_mfma_f32_16x16x32_bf16 v[90:93], v[172:175], v[188:191], v[90:93]
	v_mfma_f32_16x16x32_bf16 v[78:81], v[160:163], v[192:195], v[78:81]
	v_mfma_f32_16x16x32_bf16 v[78:81], v[164:167], v[200:203], v[78:81]
	v_mfma_f32_16x16x32_bf16 v[74:77], v[168:171], v[192:195], v[74:77]
	v_mfma_f32_16x16x32_bf16 v[74:77], v[172:175], v[200:203], v[74:77]
	v_mfma_f32_16x16x32_bf16 v[70:73], v[160:163], v[204:207], v[70:73]
	v_mfma_f32_16x16x32_bf16 v[70:73], v[164:167], v[208:211], v[70:73]
	v_mfma_f32_16x16x32_bf16 v[66:69], v[168:171], v[204:207], v[66:69]
	v_mfma_f32_16x16x32_bf16 v[66:69], v[172:175], v[208:211], v[66:69]
	s_barrier
	s_add_i32 s40, s54, s9
	v_lshl_add_u64 v[212:213], v[212:213], 0, s[12:13]
	s_mov_b32 m0, s40
	ds_read_b128 v[176:179], v143 offset:49152
	ds_read_b128 v[180:183], v143 offset:50176
	ds_read_b128 v[184:187], v143 offset:51200
	ds_read_b128 v[188:191], v143 offset:52224
	ds_read_b128 v[192:195], v143 offset:53248
	ds_read_b128 v[200:203], v143 offset:54272
	ds_read_b128 v[204:207], v143 offset:55296
	ds_read_b128 v[208:211], v143 offset:56320
	global_load_lds_dwordx4 v[212:213], off
	s_add_i32 m0, s40, 0x2000
	s_add_u32 s34, s34, 0x100080
	v_lshl_add_u64 v[212:213], v[214:215], 0, s[12:13]
	s_addc_u32 s35, s35, 0
	s_add_i32 s40, s55, s9
	global_load_lds_dwordx4 v[212:213], off
	v_lshl_add_u64 v[212:213], s[34:35], 0, v[0:1]
	s_mov_b32 m0, s40
	s_nop 0
	global_load_lds_dwordx4 v[212:213], off
	v_lshl_add_u64 v[212:213], s[34:35], 0, v[130:131]
	s_add_i32 m0, s40, 0x2000
	s_nop 0
	global_load_lds_dwordx4 v[212:213], off
	v_lshl_add_u64 v[212:213], v[216:217], 0, s[12:13]
	s_mov_b32 m0, s42
	s_nop 0
	global_load_lds_dwordx4 v[212:213], off
	v_lshl_add_u64 v[212:213], v[218:219], 0, s[12:13]
	s_mov_b32 m0, s43
	s_nop 0
	global_load_lds_dwordx4 v[212:213], off
	s_waitcnt vmcnt(8)
	s_waitcnt lgkmcnt(0)
	s_barrier
	v_mfma_f32_16x16x32_bf16 v[62:65], v[144:147], v[176:179], v[62:65]
	v_mfma_f32_16x16x32_bf16 v[62:65], v[148:151], v[180:183], v[62:65]
	v_mfma_f32_16x16x32_bf16 v[58:61], v[152:155], v[176:179], v[58:61]
	v_mfma_f32_16x16x32_bf16 v[58:61], v[156:159], v[180:183], v[58:61]
	v_mfma_f32_16x16x32_bf16 v[54:57], v[144:147], v[184:187], v[54:57]
	v_mfma_f32_16x16x32_bf16 v[54:57], v[148:151], v[188:191], v[54:57]
	v_mfma_f32_16x16x32_bf16 v[50:53], v[152:155], v[184:187], v[50:53]
	v_mfma_f32_16x16x32_bf16 v[50:53], v[156:159], v[188:191], v[50:53]
	v_mfma_f32_16x16x32_bf16 v[38:41], v[144:147], v[192:195], v[38:41]
	v_mfma_f32_16x16x32_bf16 v[38:41], v[148:151], v[200:203], v[38:41]
	v_mfma_f32_16x16x32_bf16 v[34:37], v[152:155], v[192:195], v[34:37]
	v_mfma_f32_16x16x32_bf16 v[34:37], v[156:159], v[200:203], v[34:37]
	v_mfma_f32_16x16x32_bf16 v[22:25], v[144:147], v[204:207], v[22:25]
	v_mfma_f32_16x16x32_bf16 v[22:25], v[148:151], v[208:211], v[22:25]
	v_mfma_f32_16x16x32_bf16 v[18:21], v[152:155], v[204:207], v[18:21]
	v_mfma_f32_16x16x32_bf16 v[18:21], v[156:159], v[208:211], v[18:21]
	v_mfma_f32_16x16x32_bf16 v[46:49], v[160:163], v[176:179], v[46:49]
	v_mfma_f32_16x16x32_bf16 v[46:49], v[164:167], v[180:183], v[46:49]
	v_mfma_f32_16x16x32_bf16 v[42:45], v[168:171], v[176:179], v[42:45]
	v_mfma_f32_16x16x32_bf16 v[42:45], v[172:175], v[180:183], v[42:45]
	v_mfma_f32_16x16x32_bf16 v[30:33], v[160:163], v[184:187], v[30:33]
	v_mfma_f32_16x16x32_bf16 v[30:33], v[164:167], v[188:191], v[30:33]
	v_mfma_f32_16x16x32_bf16 v[26:29], v[168:171], v[184:187], v[26:29]
	v_mfma_f32_16x16x32_bf16 v[26:29], v[172:175], v[188:191], v[26:29]
	v_mfma_f32_16x16x32_bf16 v[14:17], v[160:163], v[192:195], v[14:17]
	v_mfma_f32_16x16x32_bf16 v[14:17], v[164:167], v[200:203], v[14:17]
	v_mfma_f32_16x16x32_bf16 v[10:13], v[168:171], v[192:195], v[10:13]
	v_mfma_f32_16x16x32_bf16 v[10:13], v[172:175], v[200:203], v[10:13]
	v_mfma_f32_16x16x32_bf16 v[6:9], v[160:163], v[204:207], v[6:9]
	v_mfma_f32_16x16x32_bf16 v[6:9], v[164:167], v[208:211], v[6:9]
	v_mfma_f32_16x16x32_bf16 v[2:5], v[168:171], v[204:207], v[2:5]
	v_mfma_f32_16x16x32_bf16 v[2:5], v[172:175], v[208:211], v[2:5]
	s_barrier
	s_add_i32 s53, s53, 2
	s_add_u32 s30, s30, 0x100
	s_addc_u32 s31, s31, 0
	s_add_u32 s51, s51, 0x100
	s_addc_u32 s52, s52, 0
	s_cmp_gt_u32 s53, 61
	s_cbranch_scc0 .LBB0_801
	s_and_b64 vcc, exec, s[20:21]
	s_cbranch_vccz .LBB0_804
	s_barrier
